# attention chunk loops: quad max/sum via v_permlane16_swap/v_permlane32_swap instead of ds_bpermute (48 sites), on top of 160-tile remap
# baseline (speedup 1.0000x reference)
.LBB0_657:
	v_fma_f32 v0, v106, s46, -v165
	v_exp_f32_e32 v106, v0
	v_fma_f32 v0, v107, s46, -v165
	v_exp_f32_e32 v130, v0
	v_fma_f32 v0, v108, s46, -v165
	v_exp_f32_e32 v107, v0
	v_fma_f32 v0, v109, s46, -v165
	v_exp_f32_e32 v131, v0
	v_fma_f32 v0, v110, s46, -v165
	v_exp_f32_e32 v108, v0
	v_fma_f32 v0, v111, s46, -v165
	v_exp_f32_e32 v110, v0
	v_fma_f32 v0, v112, s46, -v165
	v_exp_f32_e32 v109, v0
	v_fma_f32 v0, v113, s46, -v165
	v_exp_f32_e32 v111, v0
	v_pk_add_f32 v[112:113], v[106:107], v[130:131]
	v_cvt_pk_bf16_f32 v106, v106, v130
	v_cvt_pk_bf16_f32 v107, v107, v131
	s_nop 0
	v_add_f32_e32 v0, v112, v113
	v_pk_add_f32 v[112:113], v[108:109], v[110:111]
	v_add_f32_e32 v133, 0, v0
	v_pk_add_f32 v[134:135], v[112:113], v[112:113] op_sel_hi:[0,1]
	v_fma_f32 v112, v115, s46, -v165
	v_exp_f32_e32 v136, v112
	v_fma_f32 v112, v116, s46, -v165
	v_fma_f32 v113, v119, s46, -v165
	v_fma_f32 v0, v114, s46, -v165
	v_exp_f32_e32 v137, v112
	v_fma_f32 v112, v117, s46, -v165
	v_exp_f32_e32 v114, v113
	v_fma_f32 v113, v120, s46, -v165
	v_exp_f32_e32 v0, v0
	v_exp_f32_e32 v164, v112
	v_fma_f32 v112, v118, s46, -v165
	v_exp_f32_e32 v134, v113
	v_fma_f32 v113, v121, s46, -v165
	v_exp_f32_e32 v112, v112
	v_exp_f32_e32 v132, v113
	v_add_f32_e32 v113, v0, v136
	v_add_f32_e32 v115, v137, v164
	v_pk_add_f32 v[116:117], v[112:113], v[114:115]
	v_pk_add_f32 v[118:119], v[134:135], v[132:133]
	v_cvt_pk_bf16_f32 v108, v108, v110
	v_cvt_pk_bf16_f32 v109, v109, v111
	v_cvt_pk_bf16_f32 v110, v0, v136
	v_cvt_pk_bf16_f32 v111, v137, v164
	v_cvt_pk_bf16_f32 v112, v112, v114
	s_nop 0
	v_pk_add_f32 v[116:117], v[116:117], v[118:119]
	s_nop 0
	v_add_f32_e32 v113, v116, v117
	v_mov_b32_e32 v115, v113
	v_mov_b32_e32 v220, v113
	s_nop 1
	v_permlane16_swap_b32_e32 v115, v220
	s_waitcnt lgkmcnt(0)
	v_add_f32_e32 v113, v115, v220
	v_mov_b32_e32 v115, v113
	v_mov_b32_e32 v221, v113
	s_nop 1
	v_permlane32_swap_b32_e32 v115, v221
	s_waitcnt lgkmcnt(0)
	v_add_f32_e32 v113, v115, v221
	v_add_f32_e32 v161, v161, v113
	v_cvt_pk_bf16_f32 v113, v134, v132
	ds_read_b64_tr_b16 v[116:117], v175 offset:18560
	ds_read_b64_tr_b16 v[114:115], v175 offset:17408
	ds_read_b64_tr_b16 v[118:119], v175 offset:17440
	ds_read_b64_tr_b16 v[120:121], v175 offset:18592
	s_waitcnt lgkmcnt(2)
	v_mfma_f32_16x16x32_bf16 v[86:89], v[114:117], v[126:129], v[86:89]
	v_mfma_f32_16x16x32_bf16 v[114:117], v[114:117], v[106:109], v[102:105]
	s_waitcnt lgkmcnt(0)
	v_mfma_f32_16x16x32_bf16 v[82:85], v[118:121], v[126:129], v[82:85]
	v_mfma_f32_16x16x32_bf16 v[118:121], v[118:121], v[106:109], v[98:101]
	s_nop 2
	ds_read_b64_tr_b16 v[98:99], v175 offset:17472
	ds_read_b64_tr_b16 v[100:101], v175 offset:18624
	s_waitcnt lgkmcnt(0)
	v_mfma_f32_16x16x32_bf16 v[130:133], v[98:101], v[106:109], v[94:97]
	s_nop 2
	ds_read_b64_tr_b16 v[94:95], v175 offset:17504
	ds_read_b64_tr_b16 v[96:97], v175 offset:18656
	v_mfma_f32_16x16x32_bf16 v[78:81], v[98:101], v[126:129], v[78:81]
	s_waitcnt lgkmcnt(0)
	v_mfma_f32_16x16x32_bf16 v[74:77], v[94:97], v[126:129], v[74:77]
	v_mfma_f32_16x16x32_bf16 v[106:109], v[94:97], v[106:109], v[90:93]
	s_nop 2
	ds_read_b64_tr_b16 v[92:93], v175 offset:27776
	ds_read_b64_tr_b16 v[90:91], v175 offset:26624
	ds_read_b64_tr_b16 v[94:95], v175 offset:26656
	ds_read_b64_tr_b16 v[96:97], v175 offset:27808
	s_add_i32 s44, s44, 4
	s_cmp_ge_u32 s45, s54
	s_waitcnt lgkmcnt(2)
	v_mfma_f32_16x16x32_bf16 v[102:105], v[90:93], v[122:125], v[86:89]
	v_mfma_f32_16x16x32_bf16 v[86:89], v[90:93], v[110:113], v[114:117]
	ds_read_b64_tr_b16 v[90:91], v175 offset:26688
	ds_read_b64_tr_b16 v[92:93], v175 offset:27840
	s_nop 0
	ds_read_b64_tr_b16 v[114:115], v175 offset:26720
	ds_read_b64_tr_b16 v[116:117], v175 offset:27872
	s_waitcnt lgkmcnt(4)
	v_mfma_f32_16x16x32_bf16 v[98:101], v[94:97], v[122:125], v[82:85]
	v_mfma_f32_16x16x32_bf16 v[82:85], v[94:97], v[110:113], v[118:121]
	s_waitcnt lgkmcnt(2)
	v_mfma_f32_16x16x32_bf16 v[94:97], v[90:93], v[122:125], v[78:81]
	v_mfma_f32_16x16x32_bf16 v[78:81], v[90:93], v[110:113], v[130:133]
	s_waitcnt lgkmcnt(0)
	v_mfma_f32_16x16x32_bf16 v[90:93], v[114:117], v[122:125], v[74:77]
	v_mfma_f32_16x16x32_bf16 v[74:77], v[114:117], v[110:113], v[106:109]
	s_cbranch_scc1 .LBB0_634
.LBB0_658:
	s_barrier
	s_waitcnt vmcnt(11)
	ds_write_b128 v170, v[26:29]
	s_waitcnt vmcnt(10)
	ds_write_b128 v171, v[30:33]
	s_waitcnt vmcnt(9)
	ds_write_b128 v172, v[34:37] offset:17408
	s_waitcnt lgkmcnt(0)
	s_barrier
	ds_read_b128 v[106:109], v173
	ds_read_b128 v[134:137], v173 offset:8832
	ds_read_b128 v[114:117], v174
	s_waitcnt lgkmcnt(2)
	v_mfma_f32_16x16x32_bf16 v[110:113], v[106:109], v[2:5], 0
	s_add_i32 s45, s44, -3
	s_min_u32 s4, s45, s55
	s_lshl_b32 s4, s4, 6
	v_mfma_f32_16x16x32_bf16 v[106:109], v[106:109], v[14:17], 0
	s_addk_i32 s4, 0xff00
	s_and_b64 s[48:49], s[40:41], exec
	s_cselect_b32 s58, 0xc0, s4
	s_waitcnt lgkmcnt(0)
	v_mfma_f32_16x16x32_bf16 v[110:113], v[114:117], v[6:9], v[110:113]
	s_mul_i32 s52, s58, 0xc00
	s_lshl_b64 s[48:49], s[58:59], 11
	ds_read_b128 v[118:121], v174 offset:1088
	v_mfma_f32_16x16x32_bf16 v[106:109], v[114:117], v[18:21], v[106:109]
	ds_read_b128 v[114:117], v173 offset:128
	s_mul_hi_u32 s4, s58, 0xc00
	s_add_u32 s52, s42, s52
	s_waitcnt lgkmcnt(0)
	v_mfma_f32_16x16x32_bf16 v[122:125], v[114:117], v[10:13], v[110:113]
	s_nop 2
	ds_read_b128 v[110:113], v173 offset:1088
	ds_read_b128 v[130:133], v174 offset:8704
	s_addc_u32 s53, s43, s4
	v_lshl_add_u64 v[26:27], v[146:147], 1, s[52:53]
	v_lshl_add_u64 v[30:31], v[148:149], 1, s[52:53]
	v_lshl_add_u64 v[26:27], v[140:141], 1, v[26:27]
	v_lshl_add_u64 v[30:31], v[142:143], 1, v[30:31]
	v_lshl_add_u64 v[34:35], v[162:163], 0, s[48:49]
	global_load_dwordx4 v[26:29], v[26:27], off
	v_mfma_f32_16x16x32_bf16 v[106:109], v[114:117], v[22:25], v[106:109]
	global_load_dwordx4 v[30:33], v[30:31], off
	ds_read_b128 v[192:195], v174 offset:9792
	global_load_dwordx4 v[34:37], v[34:35], off
	s_waitcnt lgkmcnt(2)
	v_mfma_f32_16x16x32_bf16 v[114:117], v[110:113], v[2:5], 0
	v_max_f32_e32 v0, v125, v125
	v_max_f32_e32 v164, v124, v124
	v_max_f32_e32 v0, v164, v0
	v_mfma_f32_16x16x32_bf16 v[110:113], v[110:113], v[14:17], 0
	v_max3_f32 v0, v122, v123, v0
	v_mfma_f32_16x16x32_bf16 v[114:117], v[118:121], v[6:9], v[114:117]
	v_mfma_f32_16x16x32_bf16 v[110:113], v[118:121], v[18:21], v[110:113]
	ds_read_b128 v[118:121], v173 offset:1216
	s_waitcnt lgkmcnt(0)
	v_mfma_f32_16x16x32_bf16 v[126:129], v[118:121], v[10:13], v[114:117]
	s_nop 3
	ds_read_b128 v[114:117], v173 offset:8704
	s_nop 2
	v_max_f32_e32 v164, v129, v129
	v_mfma_f32_16x16x32_bf16 v[110:113], v[118:121], v[22:25], v[110:113]
	v_max_f32_e32 v165, v128, v128
	v_max_f32_e32 v164, v165, v164
	v_max3_f32 v164, v126, v127, v164
	s_waitcnt lgkmcnt(0)
	v_mfma_f32_16x16x32_bf16 v[118:121], v[114:117], v[2:5], 0
	v_max3_f32 v0, v0, s51, v164
	v_mfma_f32_16x16x32_bf16 v[114:117], v[114:117], v[14:17], 0
	v_mfma_f32_16x16x32_bf16 v[118:121], v[130:133], v[6:9], v[118:121]
	v_mfma_f32_16x16x32_bf16 v[114:117], v[130:133], v[18:21], v[114:117]
	v_mfma_f32_16x16x32_bf16 v[130:133], v[134:137], v[10:13], v[118:121]
	s_nop 5
	ds_read_b128 v[118:121], v173 offset:9792
	v_mfma_f32_16x16x32_bf16 v[114:117], v[134:137], v[22:25], v[114:117]
	v_max_f32_e32 v164, v133, v133
	v_max_f32_e32 v165, v132, v132
	v_max_f32_e32 v164, v165, v164
	s_waitcnt lgkmcnt(0)
	v_mfma_f32_16x16x32_bf16 v[134:137], v[118:121], v[2:5], 0
	v_max3_f32 v164, v130, v131, v164
	v_mfma_f32_16x16x32_bf16 v[118:121], v[118:121], v[14:17], 0
	v_mfma_f32_16x16x32_bf16 v[134:137], v[192:195], v[6:9], v[134:137]
	v_mfma_f32_16x16x32_bf16 v[118:121], v[192:195], v[18:21], v[118:121]
	ds_read_b128 v[192:195], v173 offset:9920
	s_waitcnt lgkmcnt(0)
	v_mfma_f32_16x16x32_bf16 v[134:137], v[192:195], v[10:13], v[134:137]
	s_nop 7
	v_max_f32_e32 v165, v137, v137
	v_max_f32_e32 v168, v136, v136
	v_max_f32_e32 v165, v168, v165
	v_max3_f32 v165, v134, v135, v165
	v_max3_f32 v0, v0, v164, v165
	v_mov_b32_e32 v164, v0
	v_mov_b32_e32 v220, v0
	s_nop 1
	v_permlane16_swap_b32_e32 v164, v220
	v_mfma_f32_16x16x32_bf16 v[118:121], v[192:195], v[22:25], v[118:121]
	s_waitcnt lgkmcnt(0)
	v_max_f32_e32 v0, v164, v220
	v_mov_b32_e32 v164, v0
	v_mov_b32_e32 v221, v0
	s_nop 1
	v_permlane32_swap_b32_e32 v164, v221
	s_waitcnt lgkmcnt(0)
	v_max_f32_e32 v0, v164, v221
	v_mul_f32_e32 v0, 0x3e16c740, v0
	v_add_f32_e32 v164, 0x41000000, v166
	v_cmp_gt_f32_e32 vcc, v0, v164
	s_cbranch_vccz .LBB0_660
	s_nop 0
	v_cndmask_b32_e32 v164, v166, v0, vcc
	v_sub_f32_e32 v0, v166, v164
	v_exp_f32_e32 v0, v0
	v_mov_b32_e32 v165, v167
	v_mov_b32_e32 v166, v164
	v_mul_f32_e32 v160, v160, v0
	v_pk_mul_f32 v[104:105], v[104:105], v[0:1] op_sel_hi:[1,0]
	v_pk_mul_f32 v[102:103], v[102:103], v[0:1] op_sel_hi:[1,0]
	v_pk_mul_f32 v[100:101], v[100:101], v[0:1] op_sel_hi:[1,0]
	v_pk_mul_f32 v[98:99], v[98:99], v[0:1] op_sel_hi:[1,0]
	v_pk_mul_f32 v[96:97], v[96:97], v[0:1] op_sel_hi:[1,0]
	v_pk_mul_f32 v[94:95], v[94:95], v[0:1] op_sel_hi:[1,0]
	v_pk_mul_f32 v[92:93], v[92:93], v[0:1] op_sel_hi:[1,0]
	v_pk_mul_f32 v[90:91], v[90:91], v[0:1] op_sel_hi:[1,0]
	s_branch .LBB0_661

.LBB0_661:
	v_fma_f32 v0, v122, s46, -v166
	v_exp_f32_e32 v122, v0
	v_fma_f32 v0, v123, s46, -v166
	v_exp_f32_e32 v168, v0
	v_fma_f32 v0, v124, s46, -v166
	v_exp_f32_e32 v123, v0
	v_fma_f32 v0, v125, s46, -v166
	v_exp_f32_e32 v169, v0
	v_fma_f32 v0, v126, s46, -v166
	v_exp_f32_e32 v124, v0
	v_fma_f32 v0, v127, s46, -v166
	v_exp_f32_e32 v192, v0
	v_fma_f32 v0, v128, s46, -v166
	v_exp_f32_e32 v125, v0
	v_fma_f32 v0, v129, s46, -v166
	v_exp_f32_e32 v193, v0
	v_pk_add_f32 v[126:127], v[122:123], v[168:169]
	s_nop 0
	v_add_f32_e32 v0, v126, v127
	v_pk_add_f32 v[126:127], v[124:125], v[192:193]
	v_add_f32_e32 v167, 0, v0
	v_pk_add_f32 v[194:195], v[126:127], v[126:127] op_sel_hi:[0,1]
	v_fma_f32 v126, v131, s46, -v166
	v_exp_f32_e32 v177, v126
	v_fma_f32 v126, v132, s46, -v166
	v_exp_f32_e32 v179, v126
	v_fma_f32 v126, v133, s46, -v166
	v_exp_f32_e32 v196, v126
	v_fma_f32 v126, v134, s46, -v166
	v_fma_f32 v0, v130, s46, -v166
	v_exp_f32_e32 v130, v126
	v_fma_f32 v126, v135, s46, -v166
	v_exp_f32_e32 v132, v126
	v_fma_f32 v126, v136, s46, -v166
	v_exp_f32_e32 v0, v0
	v_exp_f32_e32 v194, v126
	v_fma_f32 v126, v137, s46, -v166
	v_exp_f32_e32 v166, v126
	v_add_f32_e32 v131, v0, v177
	v_add_f32_e32 v133, v179, v196
	v_pk_add_f32 v[126:127], v[130:131], v[132:133]
	v_pk_add_f32 v[128:129], v[194:195], v[166:167]
	s_nop 0
	v_pk_add_f32 v[126:127], v[126:127], v[128:129]
	v_max_f32_e32 v128, v112, v112
	v_add_f32_e32 v126, v126, v127
	v_mov_b32_e32 v127, v126
	v_mov_b32_e32 v222, v126
	s_nop 1
	v_permlane16_swap_b32_e32 v127, v222
	v_max_f32_e32 v129, v120, v120
	s_waitcnt lgkmcnt(0)
	v_add_f32_e32 v126, v127, v222
	v_mov_b32_e32 v127, v126
	v_mov_b32_e32 v223, v126
	s_nop 1
	v_permlane32_swap_b32_e32 v127, v223
	s_waitcnt lgkmcnt(0)
	v_add_f32_e32 v126, v127, v223
	v_add_f32_e32 v160, v160, v126
	v_max_f32_e32 v126, v109, v109
	v_max_f32_e32 v127, v108, v108
	v_max_f32_e32 v126, v127, v126
	v_max_f32_e32 v127, v113, v113
	v_max_f32_e32 v127, v128, v127
	v_max3_f32 v126, v106, v107, v126
	v_max3_f32 v127, v110, v111, v127
	v_max3_f32 v126, v126, s51, v127
	v_max_f32_e32 v127, v117, v117
	v_max_f32_e32 v128, v116, v116
	v_max_f32_e32 v127, v128, v127
	v_max_f32_e32 v128, v121, v121
	v_max_f32_e32 v128, v129, v128
	v_max3_f32 v127, v114, v115, v127
	v_max3_f32 v128, v118, v119, v128
	v_max3_f32 v131, v126, v127, v128
	v_mov_b32_e32 v133, v131
	v_mov_b32_e32 v224, v131
	s_nop 1
	v_permlane16_swap_b32_e32 v133, v224
	v_cvt_pk_bf16_f32 v126, v122, v168
	v_cvt_pk_bf16_f32 v127, v123, v169
	v_cvt_pk_bf16_f32 v128, v124, v192
	v_cvt_pk_bf16_f32 v129, v125, v193
	s_waitcnt lgkmcnt(0)
	v_max_f32_e32 v131, v133, v224
	v_mov_b32_e32 v133, v131
	v_mov_b32_e32 v225, v131
	s_nop 1
	v_permlane32_swap_b32_e32 v133, v225
	v_cvt_pk_bf16_f32 v122, v0, v177
	v_cvt_pk_bf16_f32 v123, v179, v196
	v_cvt_pk_bf16_f32 v124, v130, v132
	v_add_f32_e32 v130, 0x41000000, v165
	s_waitcnt lgkmcnt(0)
	v_max_f32_e32 v0, v133, v225
	v_mul_f32_e32 v0, 0x3e16c740, v0
	v_cmp_gt_f32_e32 vcc, v0, v130
	v_cvt_pk_bf16_f32 v125, v194, v166
	s_cbranch_vccz .LBB0_663
	s_nop 0
	v_cndmask_b32_e32 v130, v165, v0, vcc
	v_sub_f32_e32 v0, v165, v130
	v_exp_f32_e32 v0, v0
	v_mov_b32_e32 v165, v130
	v_mul_f32_e32 v161, v161, v0
	v_pk_mul_f32 v[88:89], v[88:89], v[0:1] op_sel_hi:[1,0]
	v_pk_mul_f32 v[86:87], v[86:87], v[0:1] op_sel_hi:[1,0]
	v_pk_mul_f32 v[84:85], v[84:85], v[0:1] op_sel_hi:[1,0]
	v_pk_mul_f32 v[82:83], v[82:83], v[0:1] op_sel_hi:[1,0]
	v_pk_mul_f32 v[80:81], v[80:81], v[0:1] op_sel_hi:[1,0]
	v_pk_mul_f32 v[78:79], v[78:79], v[0:1] op_sel_hi:[1,0]
	v_pk_mul_f32 v[76:77], v[76:77], v[0:1] op_sel_hi:[1,0]
	v_pk_mul_f32 v[74:75], v[74:75], v[0:1] op_sel_hi:[1,0]
.LBB0_663:
	v_fma_f32 v0, v106, s46, -v165
	v_exp_f32_e32 v106, v0
	v_fma_f32 v0, v107, s46, -v165
	v_exp_f32_e32 v130, v0
	v_fma_f32 v0, v108, s46, -v165
	v_exp_f32_e32 v107, v0
	v_fma_f32 v0, v109, s46, -v165
	v_exp_f32_e32 v131, v0
	v_fma_f32 v0, v110, s46, -v165
	v_exp_f32_e32 v108, v0
	v_fma_f32 v0, v111, s46, -v165
	v_exp_f32_e32 v110, v0
	v_fma_f32 v0, v112, s46, -v165
	v_exp_f32_e32 v109, v0
	v_fma_f32 v0, v113, s46, -v165
	v_exp_f32_e32 v111, v0
	v_pk_add_f32 v[112:113], v[106:107], v[130:131]
	v_mov_b64_e32 v[168:169], v[164:165]
	v_add_f32_e32 v0, v112, v113
	v_pk_add_f32 v[112:113], v[108:109], v[110:111]
	v_add_f32_e32 v133, 0, v0
	v_pk_add_f32 v[134:135], v[112:113], v[112:113] op_sel_hi:[0,1]
	v_fma_f32 v112, v115, s46, -v165
	v_exp_f32_e32 v136, v112
	v_fma_f32 v112, v116, s46, -v165
	v_fma_f32 v113, v119, s46, -v165
	v_fma_f32 v0, v114, s46, -v165
	v_exp_f32_e32 v137, v112
	v_fma_f32 v112, v117, s46, -v165
	v_exp_f32_e32 v114, v113
	v_fma_f32 v113, v120, s46, -v165
	v_exp_f32_e32 v0, v0
	v_exp_f32_e32 v164, v112
	v_fma_f32 v112, v118, s46, -v165
	v_exp_f32_e32 v134, v113
	v_fma_f32 v113, v121, s46, -v165
	v_exp_f32_e32 v112, v112
	v_exp_f32_e32 v132, v113
	v_add_f32_e32 v113, v0, v136
	v_add_f32_e32 v115, v137, v164
	v_pk_add_f32 v[116:117], v[112:113], v[114:115]
	v_pk_add_f32 v[118:119], v[134:135], v[132:133]
	v_cvt_pk_bf16_f32 v106, v106, v130
	v_cvt_pk_bf16_f32 v107, v107, v131
	v_cvt_pk_bf16_f32 v108, v108, v110
	v_cvt_pk_bf16_f32 v109, v109, v111
	v_cvt_pk_bf16_f32 v110, v0, v136
	s_nop 0
	v_pk_add_f32 v[116:117], v[116:117], v[118:119]
	v_cvt_pk_bf16_f32 v111, v137, v164
	v_cvt_pk_bf16_f32 v112, v112, v114
	s_nop 0
	v_add_f32_e32 v113, v116, v117
	v_mov_b32_e32 v115, v113
	v_mov_b32_e32 v228, v113
	s_nop 1
	v_permlane16_swap_b32_e32 v115, v228
	s_waitcnt lgkmcnt(0)
	v_add_f32_e32 v113, v115, v228
	v_mov_b32_e32 v115, v113
	v_mov_b32_e32 v229, v113
	s_nop 1
	v_permlane32_swap_b32_e32 v115, v229
	s_waitcnt lgkmcnt(0)
	v_add_f32_e32 v113, v115, v229
	v_add_f32_e32 v161, v161, v113
	v_cvt_pk_bf16_f32 v113, v134, v132
	ds_read_b64_tr_b16 v[116:117], v175 offset:18560
	ds_read_b64_tr_b16 v[114:115], v175 offset:17408
	ds_read_b64_tr_b16 v[118:119], v175 offset:17440
	ds_read_b64_tr_b16 v[120:121], v175 offset:18592
	s_waitcnt lgkmcnt(2)
	v_mfma_f32_16x16x32_bf16 v[102:105], v[114:117], v[126:129], v[102:105]
	v_mfma_f32_16x16x32_bf16 v[114:117], v[114:117], v[106:109], v[86:89]
	s_waitcnt lgkmcnt(0)
	v_mfma_f32_16x16x32_bf16 v[98:101], v[118:121], v[126:129], v[98:101]
	v_mfma_f32_16x16x32_bf16 v[118:121], v[118:121], v[106:109], v[82:85]
	s_nop 2
	ds_read_b64_tr_b16 v[82:83], v175 offset:17472
	ds_read_b64_tr_b16 v[84:85], v175 offset:18624
	s_waitcnt lgkmcnt(0)
	v_mfma_f32_16x16x32_bf16 v[130:133], v[82:85], v[106:109], v[78:81]
	s_nop 2
	ds_read_b64_tr_b16 v[78:79], v175 offset:17504
	ds_read_b64_tr_b16 v[80:81], v175 offset:18656
	v_mfma_f32_16x16x32_bf16 v[94:97], v[82:85], v[126:129], v[94:97]
	s_waitcnt lgkmcnt(0)
	v_mfma_f32_16x16x32_bf16 v[90:93], v[78:81], v[126:129], v[90:93]
	v_mfma_f32_16x16x32_bf16 v[106:109], v[78:81], v[106:109], v[74:77]
	s_nop 2
	ds_read_b64_tr_b16 v[76:77], v175 offset:27776
	ds_read_b64_tr_b16 v[74:75], v175 offset:26624
	ds_read_b64_tr_b16 v[78:79], v175 offset:26656
	ds_read_b64_tr_b16 v[80:81], v175 offset:27808
	s_add_i32 s4, s44, -2
	s_min_u32 s4, s4, s55
	s_waitcnt lgkmcnt(2)
	v_mfma_f32_16x16x32_bf16 v[86:89], v[74:77], v[122:125], v[102:105]
	s_lshl_b32 s4, s4, 6
	s_addk_i32 s4, 0xff00
	s_and_b64 s[48:49], s[40:41], exec
	v_mfma_f32_16x16x32_bf16 v[102:105], v[74:77], v[110:113], v[114:117]
	ds_read_b64_tr_b16 v[74:75], v175 offset:26688
	ds_read_b64_tr_b16 v[76:77], v175 offset:27840
	s_nop 0
	ds_read_b64_tr_b16 v[114:115], v175 offset:26720
	ds_read_b64_tr_b16 v[116:117], v175 offset:27872
	s_waitcnt lgkmcnt(0)
	v_mfma_f32_16x16x32_bf16 v[82:85], v[78:81], v[122:125], v[98:101]
	s_barrier
	s_waitcnt vmcnt(11)
	ds_write_b128 v170, v[38:41]
	s_waitcnt vmcnt(10)
	ds_write_b128 v171, v[42:45]
	s_waitcnt vmcnt(9)
	ds_write_b128 v172, v[46:49] offset:17408
	v_mfma_f32_16x16x32_bf16 v[98:101], v[78:81], v[110:113], v[118:121]
	s_waitcnt lgkmcnt(0)
	s_barrier
	v_mfma_f32_16x16x32_bf16 v[78:81], v[74:77], v[122:125], v[94:97]
	ds_read_b128 v[134:137], v173 offset:8832
	s_cselect_b32 s58, 0xc0, s4
	s_mul_i32 s52, s58, 0xc00
	v_mfma_f32_16x16x32_bf16 v[94:97], v[74:77], v[110:113], v[130:133]
	s_lshl_b64 s[48:49], s[58:59], 11
	ds_read_b128 v[118:121], v174 offset:1088
	s_mul_hi_u32 s4, s58, 0xc00
	v_mfma_f32_16x16x32_bf16 v[74:77], v[114:117], v[122:125], v[90:93]
	s_add_u32 s52, s42, s52
	s_addc_u32 s53, s43, s4
	v_lshl_add_u64 v[38:39], v[146:147], 1, s[52:53]
	v_mfma_f32_16x16x32_bf16 v[90:93], v[114:117], v[110:113], v[106:109]
	ds_read_b128 v[114:117], v174
	v_lshl_add_u64 v[42:43], v[148:149], 1, s[52:53]
	v_lshl_add_u64 v[38:39], v[140:141], 1, v[38:39]
	ds_read_b128 v[106:109], v173
	s_waitcnt lgkmcnt(0)
	v_mfma_f32_16x16x32_bf16 v[110:113], v[106:109], v[2:5], 0
	v_lshl_add_u64 v[42:43], v[142:143], 1, v[42:43]
	v_lshl_add_u64 v[46:47], v[162:163], 0, s[48:49]
	global_load_dwordx4 v[38:41], v[38:39], off
	v_mfma_f32_16x16x32_bf16 v[106:109], v[106:109], v[14:17], 0
	global_load_dwordx4 v[42:45], v[42:43], off
	ds_read_b128 v[130:133], v174 offset:8704
	global_load_dwordx4 v[46:49], v[46:47], off
	v_mfma_f32_16x16x32_bf16 v[110:113], v[114:117], v[6:9], v[110:113]
	ds_read_b128 v[192:195], v174 offset:9792
	v_mfma_f32_16x16x32_bf16 v[106:109], v[114:117], v[18:21], v[106:109]
	ds_read_b128 v[114:117], v173 offset:128
	s_waitcnt lgkmcnt(0)
	v_mfma_f32_16x16x32_bf16 v[122:125], v[114:117], v[10:13], v[110:113]
	s_nop 2
	ds_read_b128 v[110:113], v173 offset:1088
	s_nop 3
	v_max_f32_e32 v0, v125, v125
	v_mfma_f32_16x16x32_bf16 v[106:109], v[114:117], v[22:25], v[106:109]
	v_max_f32_e32 v164, v124, v124
	v_max_f32_e32 v0, v164, v0
	v_max3_f32 v0, v122, v123, v0
	s_waitcnt lgkmcnt(0)
	v_mfma_f32_16x16x32_bf16 v[114:117], v[110:113], v[2:5], 0
	v_mfma_f32_16x16x32_bf16 v[110:113], v[110:113], v[14:17], 0
	v_mfma_f32_16x16x32_bf16 v[114:117], v[118:121], v[6:9], v[114:117]
	v_mfma_f32_16x16x32_bf16 v[110:113], v[118:121], v[18:21], v[110:113]
	ds_read_b128 v[118:121], v173 offset:1216
	s_waitcnt lgkmcnt(0)
	v_mfma_f32_16x16x32_bf16 v[126:129], v[118:121], v[10:13], v[114:117]
	s_nop 3
	ds_read_b128 v[114:117], v173 offset:8704
	s_nop 2
	v_max_f32_e32 v164, v129, v129
	v_mfma_f32_16x16x32_bf16 v[110:113], v[118:121], v[22:25], v[110:113]
	v_max_f32_e32 v166, v128, v128
	v_max_f32_e32 v164, v166, v164
	v_max3_f32 v164, v126, v127, v164
	s_waitcnt lgkmcnt(0)
	v_mfma_f32_16x16x32_bf16 v[118:121], v[114:117], v[2:5], 0
	v_max3_f32 v0, v0, s51, v164
	v_mfma_f32_16x16x32_bf16 v[114:117], v[114:117], v[14:17], 0
	v_mfma_f32_16x16x32_bf16 v[118:121], v[130:133], v[6:9], v[118:121]
	v_mfma_f32_16x16x32_bf16 v[114:117], v[130:133], v[18:21], v[114:117]
	v_mfma_f32_16x16x32_bf16 v[130:133], v[134:137], v[10:13], v[118:121]
	s_nop 5
	ds_read_b128 v[118:121], v173 offset:9792
	v_mfma_f32_16x16x32_bf16 v[114:117], v[134:137], v[22:25], v[114:117]
	v_max_f32_e32 v164, v133, v133
	v_max_f32_e32 v166, v132, v132
	v_max_f32_e32 v164, v166, v164
	s_waitcnt lgkmcnt(0)
	v_mfma_f32_16x16x32_bf16 v[134:137], v[118:121], v[2:5], 0
	v_max3_f32 v164, v130, v131, v164
	v_mfma_f32_16x16x32_bf16 v[118:121], v[118:121], v[14:17], 0
	v_mfma_f32_16x16x32_bf16 v[134:137], v[192:195], v[6:9], v[134:137]
	v_mfma_f32_16x16x32_bf16 v[118:121], v[192:195], v[18:21], v[118:121]
	ds_read_b128 v[192:195], v173 offset:9920
	s_waitcnt lgkmcnt(0)
	v_mfma_f32_16x16x32_bf16 v[134:137], v[192:195], v[10:13], v[134:137]
	s_nop 7
	v_max_f32_e32 v166, v137, v137
	v_max_f32_e32 v167, v136, v136
	v_max_f32_e32 v166, v167, v166
	v_max3_f32 v166, v134, v135, v166
	v_max3_f32 v0, v0, v164, v166
	v_mov_b32_e32 v164, v0
	v_mov_b32_e32 v230, v0
	s_nop 1
	v_permlane16_swap_b32_e32 v164, v230
	v_mfma_f32_16x16x32_bf16 v[118:121], v[192:195], v[22:25], v[118:121]
	s_waitcnt lgkmcnt(0)
	v_max_f32_e32 v0, v164, v230
	v_mov_b32_e32 v164, v0
	v_mov_b32_e32 v231, v0
	s_nop 1
	v_permlane32_swap_b32_e32 v164, v231
	s_waitcnt lgkmcnt(0)
	v_max_f32_e32 v0, v164, v231
	v_mul_f32_e32 v0, 0x3e16c740, v0
	v_add_f32_e32 v164, 0x41000000, v168
	v_cmp_gt_f32_e32 vcc, v0, v164
	s_cbranch_vccz .LBB0_665
	s_nop 0
	v_cndmask_b32_e32 v166, v168, v0, vcc
	v_sub_f32_e32 v0, v168, v166
	v_exp_f32_e32 v0, v0
	v_mov_b32_e32 v167, v169
	v_mov_b32_e32 v165, v169
	v_mov_b32_e32 v168, v166
	v_mul_f32_e32 v160, v160, v0
	v_pk_mul_f32 v[88:89], v[88:89], v[0:1] op_sel_hi:[1,0]
	v_pk_mul_f32 v[86:87], v[86:87], v[0:1] op_sel_hi:[1,0]
	v_pk_mul_f32 v[84:85], v[84:85], v[0:1] op_sel_hi:[1,0]
	v_pk_mul_f32 v[82:83], v[82:83], v[0:1] op_sel_hi:[1,0]
	v_pk_mul_f32 v[80:81], v[80:81], v[0:1] op_sel_hi:[1,0]
	v_pk_mul_f32 v[78:79], v[78:79], v[0:1] op_sel_hi:[1,0]
	v_pk_mul_f32 v[76:77], v[76:77], v[0:1] op_sel_hi:[1,0]
	v_pk_mul_f32 v[74:75], v[74:75], v[0:1] op_sel_hi:[1,0]
	s_branch .LBB0_666

.LBB0_666:
	v_fma_f32 v0, v122, s46, -v168
	v_exp_f32_e32 v122, v0
	v_fma_f32 v0, v123, s46, -v168
	v_exp_f32_e32 v192, v0
	v_fma_f32 v0, v124, s46, -v168
	v_exp_f32_e32 v123, v0
	v_fma_f32 v0, v125, s46, -v168
	v_exp_f32_e32 v193, v0
	v_fma_f32 v0, v126, s46, -v168
	v_exp_f32_e32 v124, v0
	v_fma_f32 v0, v127, s46, -v168
	v_exp_f32_e32 v194, v0
	v_fma_f32 v0, v128, s46, -v168
	v_exp_f32_e32 v125, v0
	v_fma_f32 v0, v129, s46, -v168
	v_exp_f32_e32 v195, v0
	v_pk_add_f32 v[126:127], v[122:123], v[192:193]
	s_nop 0
	v_add_f32_e32 v0, v126, v127
	v_pk_add_f32 v[126:127], v[124:125], v[194:195]
	v_add_f32_e32 v169, 0, v0
	v_pk_add_f32 v[196:197], v[126:127], v[126:127] op_sel_hi:[0,1]
	v_fma_f32 v126, v131, s46, -v168
	v_exp_f32_e32 v164, v126
	v_fma_f32 v126, v132, s46, -v168
	v_exp_f32_e32 v177, v126
	v_fma_f32 v126, v133, s46, -v168
	v_exp_f32_e32 v179, v126
	v_fma_f32 v126, v134, s46, -v168
	v_fma_f32 v0, v130, s46, -v168
	v_exp_f32_e32 v130, v126
	v_fma_f32 v126, v135, s46, -v168
	v_exp_f32_e32 v132, v126
	v_fma_f32 v126, v136, s46, -v168
	v_exp_f32_e32 v0, v0
	v_exp_f32_e32 v196, v126
	v_fma_f32 v126, v137, s46, -v168
	v_exp_f32_e32 v168, v126
	v_add_f32_e32 v131, v0, v164
	v_add_f32_e32 v133, v177, v179
	v_pk_add_f32 v[126:127], v[130:131], v[132:133]
	v_pk_add_f32 v[128:129], v[196:197], v[168:169]
	s_nop 0
	v_pk_add_f32 v[126:127], v[126:127], v[128:129]
	v_max_f32_e32 v128, v112, v112
	v_add_f32_e32 v126, v126, v127
	v_mov_b32_e32 v127, v126
	v_mov_b32_e32 v220, v126
	s_nop 1
	v_permlane16_swap_b32_e32 v127, v220
	v_max_f32_e32 v129, v120, v120
	s_waitcnt lgkmcnt(0)
	v_add_f32_e32 v126, v127, v220
	v_mov_b32_e32 v127, v126
	v_mov_b32_e32 v221, v126
	s_nop 1
	v_permlane32_swap_b32_e32 v127, v221
	s_waitcnt lgkmcnt(0)
	v_add_f32_e32 v126, v127, v221
	v_add_f32_e32 v160, v160, v126
	v_max_f32_e32 v126, v109, v109
	v_max_f32_e32 v127, v108, v108
	v_max_f32_e32 v126, v127, v126
	v_max_f32_e32 v127, v113, v113
	v_max_f32_e32 v127, v128, v127
	v_max3_f32 v126, v106, v107, v126
	v_max3_f32 v127, v110, v111, v127
	v_max3_f32 v126, v126, s51, v127
	v_max_f32_e32 v127, v117, v117
	v_max_f32_e32 v128, v116, v116
	v_max_f32_e32 v127, v128, v127
	v_max_f32_e32 v128, v121, v121
	v_max_f32_e32 v128, v129, v128
	v_max3_f32 v127, v114, v115, v127
	v_max3_f32 v128, v118, v119, v128
	v_max3_f32 v131, v126, v127, v128
	v_mov_b32_e32 v133, v131
	v_mov_b32_e32 v222, v131
	s_nop 1
	v_permlane16_swap_b32_e32 v133, v222
	v_cvt_pk_bf16_f32 v126, v122, v192
	v_cvt_pk_bf16_f32 v127, v123, v193
	v_cvt_pk_bf16_f32 v128, v124, v194
	v_cvt_pk_bf16_f32 v129, v125, v195
	s_waitcnt lgkmcnt(0)
	v_max_f32_e32 v131, v133, v222
	v_mov_b32_e32 v133, v131
	v_mov_b32_e32 v223, v131
	s_nop 1
	v_permlane32_swap_b32_e32 v133, v223
	v_cvt_pk_bf16_f32 v122, v0, v164
	v_cvt_pk_bf16_f32 v123, v177, v179
	v_cvt_pk_bf16_f32 v124, v130, v132
	v_add_f32_e32 v130, 0x41000000, v165
	s_waitcnt lgkmcnt(0)
	v_max_f32_e32 v0, v133, v223
	v_mul_f32_e32 v0, 0x3e16c740, v0
	v_cmp_gt_f32_e32 vcc, v0, v130
	v_cvt_pk_bf16_f32 v125, v196, v168
	s_cbranch_vccz .LBB0_668
	s_nop 0
	v_cndmask_b32_e32 v167, v165, v0, vcc
	v_sub_f32_e32 v0, v165, v167
	v_exp_f32_e32 v0, v0
	v_mov_b32_e32 v165, v167
	v_mul_f32_e32 v161, v161, v0
	v_pk_mul_f32 v[104:105], v[104:105], v[0:1] op_sel_hi:[1,0]
	v_pk_mul_f32 v[102:103], v[102:103], v[0:1] op_sel_hi:[1,0]
	v_pk_mul_f32 v[100:101], v[100:101], v[0:1] op_sel_hi:[1,0]
	v_pk_mul_f32 v[98:99], v[98:99], v[0:1] op_sel_hi:[1,0]
	v_pk_mul_f32 v[96:97], v[96:97], v[0:1] op_sel_hi:[1,0]
	v_pk_mul_f32 v[94:95], v[94:95], v[0:1] op_sel_hi:[1,0]
	v_pk_mul_f32 v[92:93], v[92:93], v[0:1] op_sel_hi:[1,0]
	v_pk_mul_f32 v[90:91], v[90:91], v[0:1] op_sel_hi:[1,0]
.LBB0_668:
	v_fma_f32 v0, v106, s46, -v165
	v_exp_f32_e32 v106, v0
	v_fma_f32 v0, v107, s46, -v165
	v_exp_f32_e32 v130, v0
	v_fma_f32 v0, v108, s46, -v165
	v_exp_f32_e32 v107, v0
	v_fma_f32 v0, v109, s46, -v165
	v_exp_f32_e32 v131, v0
	v_fma_f32 v0, v110, s46, -v165
	v_exp_f32_e32 v108, v0
	v_fma_f32 v0, v111, s46, -v165
	v_exp_f32_e32 v110, v0
	v_fma_f32 v0, v112, s46, -v165
	v_exp_f32_e32 v109, v0
	v_fma_f32 v0, v113, s46, -v165
	v_exp_f32_e32 v111, v0
	v_pk_add_f32 v[112:113], v[106:107], v[130:131]
	v_cvt_pk_bf16_f32 v106, v106, v130
	v_cvt_pk_bf16_f32 v107, v107, v131
	s_nop 0
	v_add_f32_e32 v0, v112, v113
	v_pk_add_f32 v[112:113], v[108:109], v[110:111]
	v_add_f32_e32 v133, 0, v0
	v_pk_add_f32 v[134:135], v[112:113], v[112:113] op_sel_hi:[0,1]
	v_fma_f32 v112, v115, s46, -v165
	v_exp_f32_e32 v136, v112
	v_fma_f32 v112, v116, s46, -v165
	v_fma_f32 v113, v119, s46, -v165
	v_fma_f32 v0, v114, s46, -v165
	v_exp_f32_e32 v137, v112
	v_fma_f32 v112, v117, s46, -v165
	v_exp_f32_e32 v114, v113
	v_fma_f32 v113, v120, s46, -v165
	v_exp_f32_e32 v0, v0
	v_exp_f32_e32 v164, v112
	v_fma_f32 v112, v118, s46, -v165
	v_exp_f32_e32 v134, v113
	v_fma_f32 v113, v121, s46, -v165
	v_exp_f32_e32 v112, v112
	v_exp_f32_e32 v132, v113
	v_add_f32_e32 v113, v0, v136
	v_add_f32_e32 v115, v137, v164
	v_pk_add_f32 v[116:117], v[112:113], v[114:115]
	v_pk_add_f32 v[118:119], v[134:135], v[132:133]
	v_cvt_pk_bf16_f32 v108, v108, v110
	v_cvt_pk_bf16_f32 v109, v109, v111
	v_cvt_pk_bf16_f32 v110, v0, v136
	v_cvt_pk_bf16_f32 v111, v137, v164
	v_cvt_pk_bf16_f32 v112, v112, v114
	s_nop 0
	v_pk_add_f32 v[116:117], v[116:117], v[118:119]
	s_nop 0
	v_add_f32_e32 v113, v116, v117
	v_mov_b32_e32 v115, v113
	v_mov_b32_e32 v224, v113
	s_nop 1
	v_permlane16_swap_b32_e32 v115, v224
	s_waitcnt lgkmcnt(0)
	v_add_f32_e32 v113, v115, v224
	v_mov_b32_e32 v115, v113
	v_mov_b32_e32 v225, v113
	s_nop 1
	v_permlane32_swap_b32_e32 v115, v225
	s_waitcnt lgkmcnt(0)
	v_add_f32_e32 v113, v115, v225
	v_add_f32_e32 v161, v161, v113
	v_cvt_pk_bf16_f32 v113, v134, v132
	ds_read_b64_tr_b16 v[116:117], v175 offset:18560
	ds_read_b64_tr_b16 v[114:115], v175 offset:17408
	ds_read_b64_tr_b16 v[118:119], v175 offset:17440
	ds_read_b64_tr_b16 v[120:121], v175 offset:18592
	s_waitcnt lgkmcnt(2)
	v_mfma_f32_16x16x32_bf16 v[86:89], v[114:117], v[126:129], v[86:89]
	v_mfma_f32_16x16x32_bf16 v[102:105], v[114:117], v[106:109], v[102:105]
	ds_read_b64_tr_b16 v[114:115], v175 offset:17472
	ds_read_b64_tr_b16 v[116:117], v175 offset:18624
	s_waitcnt lgkmcnt(0)
	v_mfma_f32_16x16x32_bf16 v[78:81], v[114:117], v[126:129], v[78:81]
	v_mfma_f32_16x16x32_bf16 v[94:97], v[114:117], v[106:109], v[94:97]
	ds_read_b64_tr_b16 v[114:115], v175 offset:17504
	ds_read_b64_tr_b16 v[116:117], v175 offset:18656
	v_mfma_f32_16x16x32_bf16 v[82:85], v[118:121], v[126:129], v[82:85]
	v_mfma_f32_16x16x32_bf16 v[98:101], v[118:121], v[106:109], v[98:101]
	s_waitcnt lgkmcnt(0)
	v_mfma_f32_16x16x32_bf16 v[74:77], v[114:117], v[126:129], v[74:77]
	v_mfma_f32_16x16x32_bf16 v[90:93], v[114:117], v[106:109], v[90:93]
	ds_read_b64_tr_b16 v[108:109], v175 offset:27776
	ds_read_b64_tr_b16 v[106:107], v175 offset:26624
	ds_read_b64_tr_b16 v[114:115], v175 offset:26656
	ds_read_b64_tr_b16 v[116:117], v175 offset:27808
	s_add_i32 s4, s44, -1
	s_min_u32 s4, s4, s55
	s_waitcnt lgkmcnt(2)
	v_mfma_f32_16x16x32_bf16 v[86:89], v[106:109], v[122:125], v[86:89]
	s_lshl_b32 s4, s4, 6
	s_addk_i32 s4, 0xff00
	s_and_b64 s[48:49], s[40:41], exec
	v_mfma_f32_16x16x32_bf16 v[102:105], v[106:109], v[110:113], v[102:105]
	ds_read_b64_tr_b16 v[106:107], v175 offset:26688
	ds_read_b64_tr_b16 v[108:109], v175 offset:27840
	s_cselect_b32 s58, 0xc0, s4
	s_mul_i32 s52, s58, 0xc00
	s_waitcnt lgkmcnt(0)
	v_mfma_f32_16x16x32_bf16 v[78:81], v[106:109], v[122:125], v[78:81]
	s_lshl_b64 s[48:49], s[58:59], 11
	s_mul_hi_u32 s4, s58, 0xc00
	s_add_u32 s52, s42, s52
	v_mfma_f32_16x16x32_bf16 v[94:97], v[106:109], v[110:113], v[94:97]
	ds_read_b64_tr_b16 v[106:107], v175 offset:26720
	ds_read_b64_tr_b16 v[108:109], v175 offset:27872
	s_waitcnt lgkmcnt(0)
	s_barrier
	v_mfma_f32_16x16x32_bf16 v[74:77], v[106:109], v[122:125], v[74:77]
	s_waitcnt vmcnt(11)
	ds_write_b128 v170, v[50:53]
	s_waitcnt vmcnt(10)
	ds_write_b128 v171, v[54:57]
	s_waitcnt vmcnt(9)
	ds_write_b128 v172, v[58:61] offset:17408
	s_waitcnt lgkmcnt(0)
	v_mfma_f32_16x16x32_bf16 v[90:93], v[106:109], v[110:113], v[90:93]
	s_barrier
	ds_read_b128 v[106:109], v173
	ds_read_b128 v[134:137], v173 offset:8832
	v_mfma_f32_16x16x32_bf16 v[82:85], v[114:117], v[122:125], v[82:85]
	ds_read_b128 v[118:121], v174 offset:1088
	s_addc_u32 s53, s43, s4
	v_lshl_add_u64 v[50:51], v[146:147], 1, s[52:53]
	v_mfma_f32_16x16x32_bf16 v[98:101], v[114:117], v[110:113], v[98:101]
	ds_read_b128 v[114:117], v174
	v_lshl_add_u64 v[54:55], v[148:149], 1, s[52:53]
	v_lshl_add_u64 v[50:51], v[140:141], 1, v[50:51]
	s_waitcnt lgkmcnt(3)
	v_mfma_f32_16x16x32_bf16 v[110:113], v[106:109], v[2:5], 0
	v_lshl_add_u64 v[54:55], v[142:143], 1, v[54:55]
	v_lshl_add_u64 v[58:59], v[162:163], 0, s[48:49]
	global_load_dwordx4 v[50:53], v[50:51], off
	v_mfma_f32_16x16x32_bf16 v[106:109], v[106:109], v[14:17], 0
	global_load_dwordx4 v[54:57], v[54:55], off
	ds_read_b128 v[130:133], v174 offset:8704
	global_load_dwordx4 v[58:61], v[58:59], off
	s_waitcnt lgkmcnt(1)
	v_mfma_f32_16x16x32_bf16 v[110:113], v[114:117], v[6:9], v[110:113]
	ds_read_b128 v[192:195], v174 offset:9792
	v_mfma_f32_16x16x32_bf16 v[106:109], v[114:117], v[18:21], v[106:109]
	ds_read_b128 v[114:117], v173 offset:128
	s_waitcnt lgkmcnt(0)
	v_mfma_f32_16x16x32_bf16 v[122:125], v[114:117], v[10:13], v[110:113]
	s_nop 2
	ds_read_b128 v[110:113], v173 offset:1088
	s_nop 3
	v_max_f32_e32 v0, v125, v125
	v_mfma_f32_16x16x32_bf16 v[106:109], v[114:117], v[22:25], v[106:109]
	v_max_f32_e32 v164, v124, v124
	v_max_f32_e32 v0, v164, v0
	v_max3_f32 v0, v122, v123, v0
	s_waitcnt lgkmcnt(0)
	v_mfma_f32_16x16x32_bf16 v[114:117], v[110:113], v[2:5], 0
	v_mfma_f32_16x16x32_bf16 v[110:113], v[110:113], v[14:17], 0
	v_mfma_f32_16x16x32_bf16 v[114:117], v[118:121], v[6:9], v[114:117]
	v_mfma_f32_16x16x32_bf16 v[110:113], v[118:121], v[18:21], v[110:113]
	ds_read_b128 v[118:121], v173 offset:1216
	s_waitcnt lgkmcnt(0)
	v_mfma_f32_16x16x32_bf16 v[126:129], v[118:121], v[10:13], v[114:117]
	s_nop 3
	ds_read_b128 v[114:117], v173 offset:8704
	s_nop 2
	v_max_f32_e32 v164, v129, v129
	v_mfma_f32_16x16x32_bf16 v[110:113], v[118:121], v[22:25], v[110:113]
	v_max_f32_e32 v168, v128, v128
	v_max_f32_e32 v164, v168, v164
	v_max3_f32 v164, v126, v127, v164
	s_waitcnt lgkmcnt(0)
	v_mfma_f32_16x16x32_bf16 v[118:121], v[114:117], v[2:5], 0
	v_max3_f32 v0, v0, s51, v164
	v_mfma_f32_16x16x32_bf16 v[114:117], v[114:117], v[14:17], 0
	v_mfma_f32_16x16x32_bf16 v[118:121], v[130:133], v[6:9], v[118:121]
	v_mfma_f32_16x16x32_bf16 v[114:117], v[130:133], v[18:21], v[114:117]
	v_mfma_f32_16x16x32_bf16 v[130:133], v[134:137], v[10:13], v[118:121]
	s_nop 5
	ds_read_b128 v[118:121], v173 offset:9792
	v_mfma_f32_16x16x32_bf16 v[114:117], v[134:137], v[22:25], v[114:117]
	v_max_f32_e32 v164, v133, v133
	v_max_f32_e32 v168, v132, v132
	v_max_f32_e32 v164, v168, v164
	s_waitcnt lgkmcnt(0)
	v_mfma_f32_16x16x32_bf16 v[134:137], v[118:121], v[2:5], 0
	v_max3_f32 v164, v130, v131, v164
	v_mfma_f32_16x16x32_bf16 v[118:121], v[118:121], v[14:17], 0
	v_mfma_f32_16x16x32_bf16 v[134:137], v[192:195], v[6:9], v[134:137]
	v_mfma_f32_16x16x32_bf16 v[118:121], v[192:195], v[18:21], v[118:121]
	ds_read_b128 v[192:195], v173 offset:9920
	s_waitcnt lgkmcnt(0)
	v_mfma_f32_16x16x32_bf16 v[134:137], v[192:195], v[10:13], v[134:137]
	s_nop 7
	v_max_f32_e32 v168, v137, v137
	v_max_f32_e32 v169, v136, v136
	v_max_f32_e32 v168, v169, v168
	v_max3_f32 v168, v134, v135, v168
	v_max3_f32 v0, v0, v164, v168
	v_mov_b32_e32 v164, v0
	v_mov_b32_e32 v228, v0
	s_nop 1
	v_permlane16_swap_b32_e32 v164, v228
	v_mfma_f32_16x16x32_bf16 v[118:121], v[192:195], v[22:25], v[118:121]
	s_waitcnt lgkmcnt(0)
	v_max_f32_e32 v0, v164, v228
	v_mov_b32_e32 v164, v0
	v_mov_b32_e32 v229, v0
	s_nop 1
	v_permlane32_swap_b32_e32 v164, v229
	s_waitcnt lgkmcnt(0)
	v_max_f32_e32 v0, v164, v229
	v_mul_f32_e32 v0, 0x3e16c740, v0
	v_add_f32_e32 v164, 0x41000000, v166
	v_cmp_gt_f32_e32 vcc, v0, v164
	s_cbranch_vccz .LBB0_670
	s_nop 0
	v_cndmask_b32_e32 v168, v166, v0, vcc
	v_sub_f32_e32 v0, v166, v168
	v_exp_f32_e32 v0, v0
	v_mov_b32_e32 v169, v167
	v_mov_b32_e32 v165, v167
	v_mov_b32_e32 v166, v168
	v_mul_f32_e32 v160, v160, v0
	v_pk_mul_f32 v[88:89], v[88:89], v[0:1] op_sel_hi:[1,0]
	v_pk_mul_f32 v[86:87], v[86:87], v[0:1] op_sel_hi:[1,0]
	v_pk_mul_f32 v[84:85], v[84:85], v[0:1] op_sel_hi:[1,0]
	v_pk_mul_f32 v[82:83], v[82:83], v[0:1] op_sel_hi:[1,0]
	v_pk_mul_f32 v[80:81], v[80:81], v[0:1] op_sel_hi:[1,0]
	v_pk_mul_f32 v[78:79], v[78:79], v[0:1] op_sel_hi:[1,0]
	v_pk_mul_f32 v[76:77], v[76:77], v[0:1] op_sel_hi:[1,0]
	v_pk_mul_f32 v[74:75], v[74:75], v[0:1] op_sel_hi:[1,0]
	s_branch .LBB0_671

.LBB0_671:
	v_fma_f32 v0, v122, s46, -v166
	v_exp_f32_e32 v122, v0
	v_fma_f32 v0, v123, s46, -v166
	v_exp_f32_e32 v192, v0
	v_fma_f32 v0, v124, s46, -v166
	v_exp_f32_e32 v123, v0
	v_fma_f32 v0, v125, s46, -v166
	v_exp_f32_e32 v193, v0
	v_fma_f32 v0, v126, s46, -v166
	v_exp_f32_e32 v124, v0
	v_fma_f32 v0, v127, s46, -v166
	v_exp_f32_e32 v194, v0
	v_fma_f32 v0, v128, s46, -v166
	v_exp_f32_e32 v125, v0
	v_fma_f32 v0, v129, s46, -v166
	v_exp_f32_e32 v195, v0
	v_pk_add_f32 v[126:127], v[122:123], v[192:193]
	s_nop 0
	v_add_f32_e32 v0, v126, v127
	v_pk_add_f32 v[126:127], v[124:125], v[194:195]
	v_add_f32_e32 v167, 0, v0
	v_pk_add_f32 v[196:197], v[126:127], v[126:127] op_sel_hi:[0,1]
	v_fma_f32 v126, v131, s46, -v166
	v_exp_f32_e32 v164, v126
	v_fma_f32 v126, v132, s46, -v166
	v_exp_f32_e32 v177, v126
	v_fma_f32 v126, v133, s46, -v166
	v_exp_f32_e32 v179, v126
	v_fma_f32 v126, v134, s46, -v166
	v_fma_f32 v0, v130, s46, -v166
	v_exp_f32_e32 v130, v126
	v_fma_f32 v126, v135, s46, -v166
	v_exp_f32_e32 v132, v126
	v_fma_f32 v126, v136, s46, -v166
	v_exp_f32_e32 v0, v0
	v_exp_f32_e32 v196, v126
	v_fma_f32 v126, v137, s46, -v166
	v_exp_f32_e32 v166, v126
	v_add_f32_e32 v131, v0, v164
	v_add_f32_e32 v133, v177, v179
	v_pk_add_f32 v[126:127], v[130:131], v[132:133]
	v_pk_add_f32 v[128:129], v[196:197], v[166:167]
	s_nop 0
	v_pk_add_f32 v[126:127], v[126:127], v[128:129]
	v_max_f32_e32 v128, v112, v112
	v_add_f32_e32 v126, v126, v127
	v_mov_b32_e32 v127, v126
	v_mov_b32_e32 v230, v126
	s_nop 1
	v_permlane16_swap_b32_e32 v127, v230
	v_max_f32_e32 v129, v120, v120
	s_waitcnt lgkmcnt(0)
	v_add_f32_e32 v126, v127, v230
	v_mov_b32_e32 v127, v126
	v_mov_b32_e32 v231, v126
	s_nop 1
	v_permlane32_swap_b32_e32 v127, v231
	s_waitcnt lgkmcnt(0)
	v_add_f32_e32 v126, v127, v231
	v_add_f32_e32 v160, v160, v126
	v_max_f32_e32 v126, v109, v109
	v_max_f32_e32 v127, v108, v108
	v_max_f32_e32 v126, v127, v126
	v_max_f32_e32 v127, v113, v113
	v_max_f32_e32 v127, v128, v127
	v_max3_f32 v126, v106, v107, v126
	v_max3_f32 v127, v110, v111, v127
	v_max3_f32 v126, v126, s51, v127
	v_max_f32_e32 v127, v117, v117
	v_max_f32_e32 v128, v116, v116
	v_max_f32_e32 v127, v128, v127
	v_max_f32_e32 v128, v121, v121
	v_max_f32_e32 v128, v129, v128
	v_max3_f32 v127, v114, v115, v127
	v_max3_f32 v128, v118, v119, v128
	v_max3_f32 v131, v126, v127, v128
	v_mov_b32_e32 v133, v131
	v_mov_b32_e32 v220, v131
	s_nop 1
	v_permlane16_swap_b32_e32 v133, v220
	v_cvt_pk_bf16_f32 v126, v122, v192
	v_cvt_pk_bf16_f32 v127, v123, v193
	v_cvt_pk_bf16_f32 v128, v124, v194
	v_cvt_pk_bf16_f32 v129, v125, v195
	s_waitcnt lgkmcnt(0)
	v_max_f32_e32 v131, v133, v220
	v_mov_b32_e32 v133, v131
	v_mov_b32_e32 v221, v131
	s_nop 1
	v_permlane32_swap_b32_e32 v133, v221
	v_cvt_pk_bf16_f32 v122, v0, v164
	v_cvt_pk_bf16_f32 v123, v177, v179
	v_cvt_pk_bf16_f32 v124, v130, v132
	v_add_f32_e32 v130, 0x41000000, v165
	s_waitcnt lgkmcnt(0)
	v_max_f32_e32 v0, v133, v221
	v_mul_f32_e32 v0, 0x3e16c740, v0
	v_cmp_gt_f32_e32 vcc, v0, v130
	v_cvt_pk_bf16_f32 v125, v196, v166
	s_cbranch_vccz .LBB0_673
	s_nop 0
	v_cndmask_b32_e32 v169, v165, v0, vcc
	v_sub_f32_e32 v0, v165, v169
	v_exp_f32_e32 v0, v0
	v_mov_b32_e32 v165, v169
	v_mul_f32_e32 v161, v161, v0
	v_pk_mul_f32 v[104:105], v[104:105], v[0:1] op_sel_hi:[1,0]
	v_pk_mul_f32 v[102:103], v[102:103], v[0:1] op_sel_hi:[1,0]
	v_pk_mul_f32 v[100:101], v[100:101], v[0:1] op_sel_hi:[1,0]
	v_pk_mul_f32 v[98:99], v[98:99], v[0:1] op_sel_hi:[1,0]
	v_pk_mul_f32 v[96:97], v[96:97], v[0:1] op_sel_hi:[1,0]
	v_pk_mul_f32 v[94:95], v[94:95], v[0:1] op_sel_hi:[1,0]
	v_pk_mul_f32 v[92:93], v[92:93], v[0:1] op_sel_hi:[1,0]
	v_pk_mul_f32 v[90:91], v[90:91], v[0:1] op_sel_hi:[1,0]
.LBB0_673:
	v_fma_f32 v0, v106, s46, -v165
	v_exp_f32_e32 v106, v0
	v_fma_f32 v0, v107, s46, -v165
	v_exp_f32_e32 v130, v0
	v_fma_f32 v0, v108, s46, -v165
	v_exp_f32_e32 v107, v0
	v_fma_f32 v0, v109, s46, -v165
	v_exp_f32_e32 v131, v0
	v_fma_f32 v0, v110, s46, -v165
	v_exp_f32_e32 v108, v0
	v_fma_f32 v0, v111, s46, -v165
	v_exp_f32_e32 v110, v0
	v_fma_f32 v0, v112, s46, -v165
	v_exp_f32_e32 v109, v0
	v_fma_f32 v0, v113, s46, -v165
	v_exp_f32_e32 v111, v0
	v_pk_add_f32 v[112:113], v[106:107], v[130:131]
	v_cvt_pk_bf16_f32 v106, v106, v130
	v_cvt_pk_bf16_f32 v107, v107, v131
	s_nop 0
	v_add_f32_e32 v0, v112, v113
	v_pk_add_f32 v[112:113], v[108:109], v[110:111]
	v_add_f32_e32 v133, 0, v0
	v_pk_add_f32 v[134:135], v[112:113], v[112:113] op_sel_hi:[0,1]
	v_fma_f32 v112, v115, s46, -v165
	v_exp_f32_e32 v136, v112
	v_fma_f32 v112, v116, s46, -v165
	v_fma_f32 v113, v119, s46, -v165
	v_fma_f32 v0, v114, s46, -v165
	v_exp_f32_e32 v137, v112
	v_fma_f32 v112, v117, s46, -v165
	v_exp_f32_e32 v114, v113
	v_fma_f32 v113, v120, s46, -v165
	v_exp_f32_e32 v0, v0
	v_exp_f32_e32 v164, v112
	v_fma_f32 v112, v118, s46, -v165
	v_exp_f32_e32 v134, v113
	v_fma_f32 v113, v121, s46, -v165
	v_exp_f32_e32 v112, v112
	v_exp_f32_e32 v132, v113
	v_add_f32_e32 v113, v0, v136
	v_add_f32_e32 v115, v137, v164
	v_pk_add_f32 v[116:117], v[112:113], v[114:115]
	v_pk_add_f32 v[118:119], v[134:135], v[132:133]
	v_cvt_pk_bf16_f32 v108, v108, v110
	v_cvt_pk_bf16_f32 v109, v109, v111
	v_cvt_pk_bf16_f32 v110, v0, v136
	v_cvt_pk_bf16_f32 v111, v137, v164
	v_cvt_pk_bf16_f32 v112, v112, v114
	s_nop 0
	v_pk_add_f32 v[116:117], v[116:117], v[118:119]
	s_nop 0
	v_add_f32_e32 v113, v116, v117
	v_mov_b32_e32 v115, v113
	v_mov_b32_e32 v222, v113
	s_nop 1
	v_permlane16_swap_b32_e32 v115, v222
	s_waitcnt lgkmcnt(0)
	v_add_f32_e32 v113, v115, v222
	v_mov_b32_e32 v115, v113
	v_mov_b32_e32 v223, v113
	s_nop 1
	v_permlane32_swap_b32_e32 v115, v223
	s_waitcnt lgkmcnt(0)
	v_add_f32_e32 v113, v115, v223
	v_add_f32_e32 v161, v161, v113
	v_cvt_pk_bf16_f32 v113, v134, v132
	ds_read_b64_tr_b16 v[116:117], v175 offset:18560
	ds_read_b64_tr_b16 v[114:115], v175 offset:17408
	ds_read_b64_tr_b16 v[118:119], v175 offset:17440
	ds_read_b64_tr_b16 v[120:121], v175 offset:18592
	s_waitcnt lgkmcnt(2)
	v_mfma_f32_16x16x32_bf16 v[86:89], v[114:117], v[126:129], v[86:89]
	v_mfma_f32_16x16x32_bf16 v[102:105], v[114:117], v[106:109], v[102:105]
	ds_read_b64_tr_b16 v[114:115], v175 offset:17472
	ds_read_b64_tr_b16 v[116:117], v175 offset:18624
	s_waitcnt lgkmcnt(0)
	v_mfma_f32_16x16x32_bf16 v[78:81], v[114:117], v[126:129], v[78:81]
	v_mfma_f32_16x16x32_bf16 v[94:97], v[114:117], v[106:109], v[94:97]
	ds_read_b64_tr_b16 v[114:115], v175 offset:17504
	ds_read_b64_tr_b16 v[116:117], v175 offset:18656
	v_mfma_f32_16x16x32_bf16 v[82:85], v[118:121], v[126:129], v[82:85]
	v_mfma_f32_16x16x32_bf16 v[98:101], v[118:121], v[106:109], v[98:101]
	s_waitcnt lgkmcnt(0)
	v_mfma_f32_16x16x32_bf16 v[74:77], v[114:117], v[126:129], v[74:77]
	v_mfma_f32_16x16x32_bf16 v[90:93], v[114:117], v[106:109], v[90:93]
	ds_read_b64_tr_b16 v[108:109], v175 offset:27776
	ds_read_b64_tr_b16 v[106:107], v175 offset:26624
	ds_read_b64_tr_b16 v[114:115], v175 offset:26656
	ds_read_b64_tr_b16 v[116:117], v175 offset:27808
	s_min_u32 s4, s44, s55
	s_lshl_b32 s4, s4, 6
	s_waitcnt lgkmcnt(2)
	v_mfma_f32_16x16x32_bf16 v[86:89], v[106:109], v[122:125], v[86:89]
	s_addk_i32 s4, 0xff00
	s_and_b64 s[48:49], s[40:41], exec
	s_cselect_b32 s58, 0xc0, s4
	v_mfma_f32_16x16x32_bf16 v[102:105], v[106:109], v[110:113], v[102:105]
	ds_read_b64_tr_b16 v[106:107], v175 offset:26688
	ds_read_b64_tr_b16 v[108:109], v175 offset:27840
	s_mul_i32 s52, s58, 0xc00
	s_lshl_b64 s[48:49], s[58:59], 11
	s_waitcnt lgkmcnt(0)
	v_mfma_f32_16x16x32_bf16 v[78:81], v[106:109], v[122:125], v[78:81]
	s_mul_hi_u32 s4, s58, 0xc00
	s_add_u32 s52, s42, s52
	s_addc_u32 s53, s43, s4
	v_mfma_f32_16x16x32_bf16 v[94:97], v[106:109], v[110:113], v[94:97]
	ds_read_b64_tr_b16 v[106:107], v175 offset:26720
	ds_read_b64_tr_b16 v[108:109], v175 offset:27872
	s_waitcnt lgkmcnt(0)
	s_barrier
	v_mfma_f32_16x16x32_bf16 v[74:77], v[106:109], v[122:125], v[74:77]
	s_waitcnt vmcnt(11)
	ds_write_b128 v170, v[62:65]
	s_waitcnt vmcnt(10)
	ds_write_b128 v171, v[66:69]
	s_waitcnt vmcnt(9)
	ds_write_b128 v172, v[70:73] offset:17408
	s_waitcnt lgkmcnt(0)
	v_mfma_f32_16x16x32_bf16 v[90:93], v[106:109], v[110:113], v[90:93]
	s_barrier
	ds_read_b128 v[106:109], v173
	ds_read_b128 v[134:137], v173 offset:8832
	v_mfma_f32_16x16x32_bf16 v[82:85], v[114:117], v[122:125], v[82:85]
	ds_read_b128 v[118:121], v174 offset:1088
	v_lshl_add_u64 v[62:63], v[146:147], 1, s[52:53]
	v_lshl_add_u64 v[66:67], v[148:149], 1, s[52:53]
	v_mfma_f32_16x16x32_bf16 v[98:101], v[114:117], v[110:113], v[98:101]
	ds_read_b128 v[114:117], v174
	v_lshl_add_u64 v[62:63], v[140:141], 1, v[62:63]
	v_lshl_add_u64 v[66:67], v[142:143], 1, v[66:67]
	s_waitcnt lgkmcnt(3)
	v_mfma_f32_16x16x32_bf16 v[110:113], v[106:109], v[2:5], 0
	v_lshl_add_u64 v[70:71], v[162:163], 0, s[48:49]
	global_load_dwordx4 v[62:65], v[62:63], off
	ds_read_b128 v[130:133], v174 offset:8704
	v_mfma_f32_16x16x32_bf16 v[106:109], v[106:109], v[14:17], 0
	global_load_dwordx4 v[66:69], v[66:67], off
	ds_read_b128 v[192:195], v174 offset:9792
	global_load_dwordx4 v[70:73], v[70:71], off
	s_waitcnt lgkmcnt(2)
	v_mfma_f32_16x16x32_bf16 v[110:113], v[114:117], v[6:9], v[110:113]
	v_mfma_f32_16x16x32_bf16 v[106:109], v[114:117], v[18:21], v[106:109]
	ds_read_b128 v[114:117], v173 offset:128
	s_waitcnt lgkmcnt(0)
	v_mfma_f32_16x16x32_bf16 v[122:125], v[114:117], v[10:13], v[110:113]
	s_nop 3
	ds_read_b128 v[110:113], v173 offset:1088
	s_nop 2
	v_max_f32_e32 v0, v125, v125
	v_mfma_f32_16x16x32_bf16 v[106:109], v[114:117], v[22:25], v[106:109]
	v_max_f32_e32 v164, v124, v124
	v_max_f32_e32 v0, v164, v0
	v_max3_f32 v0, v122, v123, v0
	s_waitcnt lgkmcnt(0)
	v_mfma_f32_16x16x32_bf16 v[114:117], v[110:113], v[2:5], 0
	v_mfma_f32_16x16x32_bf16 v[110:113], v[110:113], v[14:17], 0
	v_mfma_f32_16x16x32_bf16 v[114:117], v[118:121], v[6:9], v[114:117]
	v_mfma_f32_16x16x32_bf16 v[110:113], v[118:121], v[18:21], v[110:113]
	ds_read_b128 v[118:121], v173 offset:1216
	s_waitcnt lgkmcnt(0)
	v_mfma_f32_16x16x32_bf16 v[126:129], v[118:121], v[10:13], v[114:117]
	s_nop 3
	ds_read_b128 v[114:117], v173 offset:8704
	s_nop 2
	v_max_f32_e32 v164, v129, v129
	v_mfma_f32_16x16x32_bf16 v[110:113], v[118:121], v[22:25], v[110:113]
	v_max_f32_e32 v166, v128, v128
	v_max_f32_e32 v164, v166, v164
	v_max3_f32 v164, v126, v127, v164
	s_waitcnt lgkmcnt(0)
	v_mfma_f32_16x16x32_bf16 v[118:121], v[114:117], v[2:5], 0
	v_max3_f32 v0, v0, s51, v164
	v_mfma_f32_16x16x32_bf16 v[114:117], v[114:117], v[14:17], 0
	v_mfma_f32_16x16x32_bf16 v[118:121], v[130:133], v[6:9], v[118:121]
	v_mfma_f32_16x16x32_bf16 v[114:117], v[130:133], v[18:21], v[114:117]
	v_mfma_f32_16x16x32_bf16 v[130:133], v[134:137], v[10:13], v[118:121]
	s_nop 5
	ds_read_b128 v[118:121], v173 offset:9792
	v_mfma_f32_16x16x32_bf16 v[114:117], v[134:137], v[22:25], v[114:117]
	v_max_f32_e32 v164, v133, v133
	v_max_f32_e32 v166, v132, v132
	v_max_f32_e32 v164, v166, v164
	s_waitcnt lgkmcnt(0)
	v_mfma_f32_16x16x32_bf16 v[134:137], v[118:121], v[2:5], 0
	v_max3_f32 v164, v130, v131, v164
	v_mfma_f32_16x16x32_bf16 v[118:121], v[118:121], v[14:17], 0
	v_mfma_f32_16x16x32_bf16 v[134:137], v[192:195], v[6:9], v[134:137]
	v_mfma_f32_16x16x32_bf16 v[118:121], v[192:195], v[18:21], v[118:121]
	ds_read_b128 v[192:195], v173 offset:9920
	s_waitcnt lgkmcnt(0)
	v_mfma_f32_16x16x32_bf16 v[134:137], v[192:195], v[10:13], v[134:137]
	s_nop 7
	v_max_f32_e32 v166, v137, v137
	v_max_f32_e32 v167, v136, v136
	v_max_f32_e32 v166, v167, v166
	v_max3_f32 v166, v134, v135, v166
	v_max3_f32 v0, v0, v164, v166
	v_mov_b32_e32 v164, v0
	v_mov_b32_e32 v224, v0
	s_nop 1
	v_permlane16_swap_b32_e32 v164, v224
	v_mfma_f32_16x16x32_bf16 v[118:121], v[192:195], v[22:25], v[118:121]
	s_waitcnt lgkmcnt(0)
	v_max_f32_e32 v0, v164, v224
	v_mov_b32_e32 v164, v0
	v_mov_b32_e32 v225, v0
	s_nop 1
	v_permlane32_swap_b32_e32 v164, v225
	s_waitcnt lgkmcnt(0)
	v_max_f32_e32 v0, v164, v225
	v_mul_f32_e32 v0, 0x3e16c740, v0
	v_add_f32_e32 v164, 0x41000000, v168
	v_cmp_gt_f32_e32 vcc, v0, v164
	s_cbranch_vccz .LBB0_675
	s_nop 0
	v_cndmask_b32_e32 v166, v168, v0, vcc
	v_sub_f32_e32 v0, v168, v166
	v_exp_f32_e32 v0, v0
	v_mov_b32_e32 v167, v169
	v_mov_b32_e32 v165, v169
	v_mov_b32_e32 v168, v166
	v_mul_f32_e32 v160, v160, v0
	v_pk_mul_f32 v[88:89], v[88:89], v[0:1] op_sel_hi:[1,0]
	v_pk_mul_f32 v[86:87], v[86:87], v[0:1] op_sel_hi:[1,0]
	v_pk_mul_f32 v[84:85], v[84:85], v[0:1] op_sel_hi:[1,0]
	v_pk_mul_f32 v[82:83], v[82:83], v[0:1] op_sel_hi:[1,0]
	v_pk_mul_f32 v[80:81], v[80:81], v[0:1] op_sel_hi:[1,0]
	v_pk_mul_f32 v[78:79], v[78:79], v[0:1] op_sel_hi:[1,0]
	v_pk_mul_f32 v[76:77], v[76:77], v[0:1] op_sel_hi:[1,0]
	v_pk_mul_f32 v[74:75], v[74:75], v[0:1] op_sel_hi:[1,0]
	s_branch .LBB0_676

.LBB0_676:
	v_fma_f32 v0, v122, s46, -v168
	v_exp_f32_e32 v122, v0
	v_fma_f32 v0, v123, s46, -v168
	v_exp_f32_e32 v192, v0
	v_fma_f32 v0, v124, s46, -v168
	v_exp_f32_e32 v123, v0
	v_fma_f32 v0, v125, s46, -v168
	v_exp_f32_e32 v193, v0
	v_fma_f32 v0, v126, s46, -v168
	v_exp_f32_e32 v124, v0
	v_fma_f32 v0, v127, s46, -v168
	v_exp_f32_e32 v194, v0
	v_fma_f32 v0, v128, s46, -v168
	v_exp_f32_e32 v125, v0
	v_fma_f32 v0, v129, s46, -v168
	v_exp_f32_e32 v195, v0
	v_pk_add_f32 v[126:127], v[122:123], v[192:193]
	s_nop 0
	v_add_f32_e32 v0, v126, v127
	v_pk_add_f32 v[126:127], v[124:125], v[194:195]
	v_add_f32_e32 v169, 0, v0
	v_pk_add_f32 v[196:197], v[126:127], v[126:127] op_sel_hi:[0,1]
	v_fma_f32 v126, v131, s46, -v168
	v_exp_f32_e32 v164, v126
	v_fma_f32 v126, v132, s46, -v168
	v_exp_f32_e32 v177, v126
	v_fma_f32 v126, v133, s46, -v168
	v_exp_f32_e32 v179, v126
	v_fma_f32 v126, v134, s46, -v168
	v_fma_f32 v0, v130, s46, -v168
	v_exp_f32_e32 v130, v126
	v_fma_f32 v126, v135, s46, -v168
	v_exp_f32_e32 v132, v126
	v_fma_f32 v126, v136, s46, -v168
	v_exp_f32_e32 v0, v0
	v_exp_f32_e32 v196, v126
	v_fma_f32 v126, v137, s46, -v168
	v_exp_f32_e32 v168, v126
	v_add_f32_e32 v131, v0, v164
	v_add_f32_e32 v133, v177, v179
	v_pk_add_f32 v[126:127], v[130:131], v[132:133]
	v_pk_add_f32 v[128:129], v[196:197], v[168:169]
	s_nop 0
	v_pk_add_f32 v[126:127], v[126:127], v[128:129]
	v_max_f32_e32 v128, v112, v112
	v_add_f32_e32 v126, v126, v127
	v_mov_b32_e32 v127, v126
	v_mov_b32_e32 v228, v126
	s_nop 1
	v_permlane16_swap_b32_e32 v127, v228
	v_max_f32_e32 v129, v120, v120
	s_waitcnt lgkmcnt(0)
	v_add_f32_e32 v126, v127, v228
	v_mov_b32_e32 v127, v126
	v_mov_b32_e32 v229, v126
	s_nop 1
	v_permlane32_swap_b32_e32 v127, v229
	s_waitcnt lgkmcnt(0)
	v_add_f32_e32 v126, v127, v229
	v_add_f32_e32 v160, v160, v126
	v_max_f32_e32 v126, v109, v109
	v_max_f32_e32 v127, v108, v108
	v_max_f32_e32 v126, v127, v126
	v_max_f32_e32 v127, v113, v113
	v_max_f32_e32 v127, v128, v127
	v_max3_f32 v126, v106, v107, v126
	v_max3_f32 v127, v110, v111, v127
	v_max3_f32 v126, v126, s51, v127
	v_max_f32_e32 v127, v117, v117
	v_max_f32_e32 v128, v116, v116
	v_max_f32_e32 v127, v128, v127
	v_max_f32_e32 v128, v121, v121
	v_max_f32_e32 v128, v129, v128
	v_max3_f32 v127, v114, v115, v127
	v_max3_f32 v128, v118, v119, v128
	v_max3_f32 v131, v126, v127, v128
	v_mov_b32_e32 v133, v131
	v_mov_b32_e32 v230, v131
	s_nop 1
	v_permlane16_swap_b32_e32 v133, v230
	v_cvt_pk_bf16_f32 v126, v122, v192
	v_cvt_pk_bf16_f32 v127, v123, v193
	v_cvt_pk_bf16_f32 v128, v124, v194
	v_cvt_pk_bf16_f32 v129, v125, v195
	s_waitcnt lgkmcnt(0)
	v_max_f32_e32 v131, v133, v230
	v_mov_b32_e32 v133, v131
	v_mov_b32_e32 v231, v131
	s_nop 1
	v_permlane32_swap_b32_e32 v133, v231
	v_cvt_pk_bf16_f32 v122, v0, v164
	v_cvt_pk_bf16_f32 v123, v177, v179
	v_cvt_pk_bf16_f32 v124, v130, v132
	v_add_f32_e32 v130, 0x41000000, v165
	s_waitcnt lgkmcnt(0)
	v_max_f32_e32 v0, v133, v231
	v_mul_f32_e32 v0, 0x3e16c740, v0
	v_cmp_gt_f32_e32 vcc, v0, v130
	v_cvt_pk_bf16_f32 v125, v196, v168
	s_cbranch_vccz .LBB0_657
	s_nop 0
	v_cndmask_b32_e32 v167, v165, v0, vcc
	v_sub_f32_e32 v0, v165, v167
	v_exp_f32_e32 v0, v0
	v_mov_b32_e32 v165, v167
	v_mul_f32_e32 v161, v161, v0
	v_pk_mul_f32 v[104:105], v[104:105], v[0:1] op_sel_hi:[1,0]
	v_pk_mul_f32 v[102:103], v[102:103], v[0:1] op_sel_hi:[1,0]
	v_pk_mul_f32 v[100:101], v[100:101], v[0:1] op_sel_hi:[1,0]
	v_pk_mul_f32 v[98:99], v[98:99], v[0:1] op_sel_hi:[1,0]
	v_pk_mul_f32 v[96:97], v[96:97], v[0:1] op_sel_hi:[1,0]
	v_pk_mul_f32 v[94:95], v[94:95], v[0:1] op_sel_hi:[1,0]
	v_pk_mul_f32 v[92:93], v[92:93], v[0:1] op_sel_hi:[1,0]
	v_pk_mul_f32 v[90:91], v[90:91], v[0:1] op_sel_hi:[1,0]
	s_branch .LBB0_657

.LBB0_1074:
	v_add_f32_e32 v3, v194, v221
	v_add_f32_e32 v195, v0, v3
	v_fmamk_f32 v0, v124, 0x3e38aa3b, v196
	v_exp_f32_e32 v124, v0
	v_fmamk_f32 v0, v125, 0x3e38aa3b, v196
	v_exp_f32_e32 v200, v0
	v_fmamk_f32 v0, v126, 0x3e38aa3b, v196
	v_exp_f32_e32 v125, v0
	v_fmamk_f32 v0, v127, 0x3e38aa3b, v196
	v_exp_f32_e32 v201, v0
	v_fmamk_f32 v3, v133, 0x3e38aa3b, v196
	v_exp_f32_e32 v3, v3
	v_pk_add_f32 v[126:127], v[124:125], v[200:201]
	s_nop 0
	v_add_f32_e32 v0, v126, v127
	v_add_f32_e32 v197, 0, v0
	v_fmamk_f32 v0, v128, 0x3e38aa3b, v196
	v_exp_f32_e32 v126, v0
	v_fmamk_f32 v0, v129, 0x3e38aa3b, v196
	v_exp_f32_e32 v202, v0
	v_fmamk_f32 v0, v130, 0x3e38aa3b, v196
	v_exp_f32_e32 v127, v0
	v_fmamk_f32 v0, v131, 0x3e38aa3b, v196
	v_exp_f32_e32 v203, v0
	v_fmamk_f32 v0, v132, 0x3e38aa3b, v196
	v_exp_f32_e32 v0, v0
	v_pk_add_f32 v[128:129], v[126:127], v[202:203]
	s_nop 0
	v_pk_add_f32 v[204:205], v[128:129], v[128:129] op_sel_hi:[0,1]
	v_fmamk_f32 v128, v134, 0x3e38aa3b, v196
	v_exp_f32_e32 v194, v128
	v_fmamk_f32 v128, v135, 0x3e38aa3b, v196
	v_exp_f32_e32 v199, v128
	v_fmamk_f32 v128, v136, 0x3e38aa3b, v196
	v_exp_f32_e32 v132, v128
	v_fmamk_f32 v128, v137, 0x3e38aa3b, v196
	v_exp_f32_e32 v134, v128
	v_fmamk_f32 v128, v138, 0x3e38aa3b, v196
	v_fmac_f32_e32 v196, 0x3e38aa3b, v139
	v_exp_f32_e32 v204, v128
	v_exp_f32_e32 v196, v196
	v_add_f32_e32 v133, v0, v3
	v_add_f32_e32 v135, v194, v199
	v_pk_add_f32 v[128:129], v[132:133], v[134:135]
	v_pk_add_f32 v[130:131], v[204:205], v[196:197]
	s_nop 0
	v_pk_add_f32 v[128:129], v[128:129], v[130:131]
	s_nop 0
	v_add_f32_e32 v128, v128, v129
	v_mov_b32_e32 v129, v128
	v_mov_b32_e32 v224, v128
	s_nop 1
	v_permlane16_swap_b32_e32 v129, v224
	s_waitcnt lgkmcnt(0)
	v_add_f32_e32 v128, v129, v224
	v_mov_b32_e32 v129, v128
	v_mov_b32_e32 v225, v128
	s_nop 1
	v_permlane32_swap_b32_e32 v129, v225
	s_waitcnt lgkmcnt(0)
	v_add_f32_e32 v133, v129, v225
	v_cvt_pk_bf16_f32 v128, v124, v200
	v_cvt_pk_bf16_f32 v129, v125, v201
	v_cvt_pk_bf16_f32 v130, v126, v202
	v_cvt_pk_bf16_f32 v131, v127, v203
	v_cvt_pk_bf16_f32 v124, v0, v3
	v_cvt_pk_bf16_f32 v125, v194, v199
	v_add_f32_e32 v194, v2, v133
	v_cvt_pk_bf16_f32 v126, v132, v134
	v_cvt_pk_bf16_f32 v127, v204, v196
	ds_read_b64_tr_b16 v[134:135], v174 offset:18560
	ds_read_b64_tr_b16 v[132:133], v174 offset:17408
	ds_read_b64_tr_b16 v[136:137], v174 offset:17440
	ds_read_b64_tr_b16 v[138:139], v174 offset:18592
	s_waitcnt lgkmcnt(2)
	v_mfma_f32_16x16x32_bf16 v[68:71], v[132:135], v[120:123], v[68:71]
	v_mfma_f32_16x16x32_bf16 v[80:83], v[132:135], v[128:131], v[80:83]
	ds_read_b64_tr_b16 v[132:133], v174 offset:17472
	ds_read_b64_tr_b16 v[134:135], v174 offset:18624
	s_waitcnt lgkmcnt(0)
	v_mfma_f32_16x16x32_bf16 v[84:87], v[132:135], v[120:123], v[84:87]
	v_mfma_f32_16x16x32_bf16 v[88:91], v[132:135], v[128:131], v[88:91]
	ds_read_b64_tr_b16 v[132:133], v174 offset:17504
	ds_read_b64_tr_b16 v[134:135], v174 offset:18656
	s_waitcnt lgkmcnt(0)
	v_mfma_f32_16x16x32_bf16 v[52:55], v[132:135], v[120:123], v[52:55]
	v_mfma_f32_16x16x32_bf16 v[56:59], v[132:135], v[128:131], v[56:59]
	ds_read_b64_tr_b16 v[132:133], v175 offset:17408
	ds_read_b64_tr_b16 v[134:135], v175 offset:18560
	v_mfma_f32_16x16x32_bf16 v[64:67], v[136:139], v[120:123], v[64:67]
	v_mfma_f32_16x16x32_bf16 v[76:79], v[136:139], v[128:131], v[76:79]
	s_waitcnt lgkmcnt(0)
	v_mfma_f32_16x16x32_bf16 v[136:139], v[132:135], v[120:123], v[92:95]
	s_nop 2
	ds_read_b64_tr_b16 v[92:93], v176 offset:17408
	ds_read_b64_tr_b16 v[94:95], v176 offset:18560
	s_waitcnt lgkmcnt(0)
	v_mfma_f32_16x16x32_bf16 v[200:203], v[92:95], v[128:131], v[72:75]
	s_nop 2
	ds_read_b64_tr_b16 v[72:73], v177 offset:17408
	ds_read_b64_tr_b16 v[74:75], v177 offset:18560
	s_waitcnt lgkmcnt(0)
	v_mfma_f32_16x16x32_bf16 v[204:207], v[72:75], v[120:123], v[108:111]
	v_mfma_f32_16x16x32_bf16 v[208:211], v[72:75], v[128:131], v[112:115]
	ds_read_b64_tr_b16 v[72:73], v192 offset:17408
	ds_read_b64_tr_b16 v[74:75], v192 offset:18560
	v_mfma_f32_16x16x32_bf16 v[60:63], v[92:95], v[120:123], v[60:63]
	v_mfma_f32_16x16x32_bf16 v[132:135], v[132:135], v[128:131], v[96:99]
	s_waitcnt lgkmcnt(0)
	v_mfma_f32_16x16x32_bf16 v[120:123], v[72:75], v[120:123], v[100:103]
	v_mfma_f32_16x16x32_bf16 v[128:131], v[72:75], v[128:131], v[104:107]
	ds_read_b64_tr_b16 v[74:75], v174 offset:27776
	ds_read_b64_tr_b16 v[72:73], v174 offset:26624
	ds_read_b64_tr_b16 v[92:93], v174 offset:26656
	ds_read_b64_tr_b16 v[94:95], v174 offset:27808
	s_add_i32 s45, s45, 2
	s_cmp_ge_u32 s47, s43
	s_waitcnt lgkmcnt(2)
	v_mfma_f32_16x16x32_bf16 v[108:111], v[72:75], v[124:127], v[80:83]
	v_mfma_f32_16x16x32_bf16 v[112:115], v[72:75], v[116:119], v[68:71]
	s_waitcnt lgkmcnt(0)
	v_mfma_f32_16x16x32_bf16 v[104:107], v[92:95], v[116:119], v[64:67]
	s_nop 2
	ds_read_b64_tr_b16 v[64:65], v174 offset:26688
	ds_read_b64_tr_b16 v[66:67], v174 offset:27840
	v_mfma_f32_16x16x32_bf16 v[100:103], v[92:95], v[124:127], v[76:79]
	s_waitcnt lgkmcnt(0)
	v_mfma_f32_16x16x32_bf16 v[96:99], v[64:67], v[116:119], v[84:87]
	v_mfma_f32_16x16x32_bf16 v[92:95], v[64:67], v[124:127], v[88:91]
	ds_read_b64_tr_b16 v[64:65], v174 offset:26720
	ds_read_b64_tr_b16 v[66:67], v174 offset:27872
	s_waitcnt lgkmcnt(0)
	v_mfma_f32_16x16x32_bf16 v[88:91], v[64:67], v[116:119], v[52:55]
	s_nop 2
	ds_read_b64_tr_b16 v[52:53], v175 offset:26624
	ds_read_b64_tr_b16 v[54:55], v175 offset:27776
	s_waitcnt lgkmcnt(0)
	v_mfma_f32_16x16x32_bf16 v[80:83], v[52:55], v[116:119], v[136:139]
	v_mfma_f32_16x16x32_bf16 v[76:79], v[52:55], v[124:127], v[132:135]
	ds_read_b64_tr_b16 v[52:53], v176 offset:26624
	ds_read_b64_tr_b16 v[54:55], v176 offset:27776
	s_waitcnt lgkmcnt(0)
	v_mfma_f32_16x16x32_bf16 v[72:75], v[52:55], v[116:119], v[60:63]
	v_mfma_f32_16x16x32_bf16 v[68:71], v[52:55], v[124:127], v[200:203]
	ds_read_b64_tr_b16 v[52:53], v177 offset:26624
	ds_read_b64_tr_b16 v[54:55], v177 offset:27776
	v_mfma_f32_16x16x32_bf16 v[84:87], v[64:67], v[124:127], v[56:59]
	s_waitcnt lgkmcnt(0)
	v_mfma_f32_16x16x32_bf16 v[64:67], v[52:55], v[116:119], v[204:207]
	v_mfma_f32_16x16x32_bf16 v[56:59], v[52:55], v[124:127], v[208:211]
	ds_read_b64_tr_b16 v[52:53], v192 offset:26624
	ds_read_b64_tr_b16 v[54:55], v192 offset:27776
	s_waitcnt lgkmcnt(0)
	v_mfma_f32_16x16x32_bf16 v[60:63], v[52:55], v[116:119], v[120:123]
	v_mfma_f32_16x16x32_bf16 v[52:55], v[52:55], v[124:127], v[128:131]
	s_cbranch_scc1 .LBB0_1054
.LBB0_1075:
	s_barrier
	s_waitcnt vmcnt(7)
	ds_write_b128 v167, v[28:31]
	s_waitcnt vmcnt(6)
	ds_write_b128 v168, v[32:35]
	s_waitcnt vmcnt(5)
	ds_write_b128 v169, v[44:47] offset:17408
	s_waitcnt vmcnt(4)
	ds_write_b128 v170, v[48:51] offset:17408
	s_waitcnt lgkmcnt(0)
	s_barrier
	ds_read_b128 v[28:31], v171
	ds_read_b128 v[44:47], v171 offset:1088
	ds_read_b128 v[32:35], v172
	s_add_i32 s47, s45, -1
	ds_read_b128 v[48:51], v172 offset:1088
	s_min_u32 s4, s47, s44
	s_waitcnt lgkmcnt(3)
	v_mfma_f32_16x16x32_bf16 v[28:31], v[28:31], v[4:7], 0
	s_lshl_b32 s54, s4, 6
	s_cmp_lt_u32 s4, 4
	s_cselect_b64 s[48:49], -1, 0
	s_add_i32 s4, s54, 0xffffff00
	s_and_b64 s[52:53], s[48:49], exec
	s_waitcnt lgkmcnt(1)
	v_mfma_f32_16x16x32_bf16 v[128:131], v[32:35], v[8:11], v[28:31]
	s_cselect_b32 s58, s54, s4
	s_cselect_b32 s4, s27, s15
	s_cselect_b32 s54, s26, s14
	v_mfma_f32_16x16x32_bf16 v[28:31], v[44:47], v[4:7], 0
	ds_read_b128 v[44:47], v171 offset:8704
	s_lshl_b64 s[52:53], s[58:59], 11
	s_add_u32 s54, s54, s52
	s_addc_u32 s4, s4, s53
	s_waitcnt lgkmcnt(1)
	v_mfma_f32_16x16x32_bf16 v[124:127], v[48:51], v[8:11], v[28:31]
	ds_read_b128 v[48:51], v172 offset:8704
	s_and_b64 s[48:49], s[48:49], exec
	s_cselect_b32 s49, s36, s24
	s_cselect_b32 s48, s37, s25
	s_add_u32 s52, s49, s52
	s_addc_u32 s53, s48, s53
	s_add_u32 s48, s54, s40
	s_waitcnt lgkmcnt(1)
	v_mfma_f32_16x16x32_bf16 v[44:47], v[44:47], v[4:7], 0
	s_addc_u32 s49, s4, s41
	v_lshl_add_u64 v[2:3], v[152:153], 1, s[48:49]
	v_lshl_add_u64 v[32:33], v[154:155], 1, s[48:49]
	s_add_u32 s48, s52, s40
	v_lshl_add_u64 v[2:3], v[140:141], 1, v[2:3]
	v_lshl_add_u64 v[32:33], v[142:143], 1, v[32:33]
	s_addc_u32 s49, s53, s41
	global_load_dwordx4 v[28:31], v[2:3], off
	s_nop 0
	global_load_dwordx4 v[32:35], v[32:33], off
	v_lshl_add_u64 v[2:3], v[150:151], 1, s[48:49]
	s_waitcnt lgkmcnt(0)
	v_mfma_f32_16x16x32_bf16 v[120:123], v[48:51], v[8:11], v[44:47]
	v_lshl_add_u64 v[2:3], v[144:145], 1, v[2:3]
	ds_read_b128 v[116:119], v171 offset:9792
	ds_read_b128 v[132:135], v172 offset:9792
	v_lshl_add_u64 v[44:45], v[156:157], 1, s[48:49]
	v_lshl_add_u64 v[48:49], v[146:147], 1, v[44:45]
	global_load_dwordx4 v[44:47], v[2:3], off
	s_nop 0
	global_load_dwordx4 v[48:51], v[48:49], off
	s_waitcnt lgkmcnt(1)
	v_mfma_f32_16x16x32_bf16 v[116:119], v[116:119], v[4:7], 0
	v_max_f32_e32 v0, v131, v131
	v_max_f32_e32 v2, v130, v130
	v_max_f32_e32 v0, v2, v0
	s_waitcnt lgkmcnt(0)
	v_mfma_f32_16x16x32_bf16 v[116:119], v[132:135], v[8:11], v[116:119]
	v_max_f32_e32 v2, v127, v127
	v_max_f32_e32 v3, v126, v126
	v_max_f32_e32 v2, v3, v2
	v_max3_f32 v0, v128, v129, v0
	v_max3_f32 v2, v124, v125, v2
	v_max3_f32 v0, v0, s51, v2
	v_max_f32_e32 v2, v123, v123
	v_max_f32_e32 v3, v122, v122
	v_max_f32_e32 v2, v3, v2
	v_max_f32_e32 v3, v119, v119
	v_max_f32_e32 v132, v118, v118
	v_max_f32_e32 v3, v132, v3
	v_max3_f32 v2, v120, v121, v2
	v_max3_f32 v3, v116, v117, v3
	v_max3_f32 v0, v0, v2, v3
	v_mov_b32_e32 v2, v0
	v_mov_b32_e32 v220, v0
	s_nop 1
	v_permlane16_swap_b32_e32 v2, v220
	s_waitcnt lgkmcnt(0)
	v_max_f32_e32 v0, v2, v220
	v_mov_b32_e32 v2, v0
	v_mov_b32_e32 v221, v0
	s_nop 1
	v_permlane32_swap_b32_e32 v2, v221
	s_waitcnt lgkmcnt(0)
	v_max_f32_e32 v0, v2, v221
	v_mul_f32_e32 v0, 0x3e38aa3b, v0
	v_add_f32_e32 v2, 0x41000000, v193
	v_cmp_gt_f32_e32 vcc, v0, v2
	s_cbranch_vccz .LBB0_1077
	s_nop 0
	v_cndmask_b32_e32 v2, v193, v0, vcc
	v_sub_f32_e32 v0, v193, v2
	v_exp_f32_e32 v0, v0
	v_mov_b32_e32 v193, v2
	v_pk_mul_f32 v[114:115], v[114:115], v[0:1] op_sel_hi:[1,0]
	v_pk_mul_f32 v[112:113], v[112:113], v[0:1] op_sel_hi:[1,0]
	v_pk_mul_f32 v[106:107], v[106:107], v[0:1] op_sel_hi:[1,0]
	v_pk_mul_f32 v[104:105], v[104:105], v[0:1] op_sel_hi:[1,0]
	v_pk_mul_f32 v[98:99], v[98:99], v[0:1] op_sel_hi:[1,0]
	v_pk_mul_f32 v[96:97], v[96:97], v[0:1] op_sel_hi:[1,0]
	v_pk_mul_f32 v[90:91], v[90:91], v[0:1] op_sel_hi:[1,0]
	v_pk_mul_f32 v[88:89], v[88:89], v[0:1] op_sel_hi:[1,0]
	v_pk_mul_f32 v[82:83], v[82:83], v[0:1] op_sel_hi:[1,0]
	v_pk_mul_f32 v[80:81], v[80:81], v[0:1] op_sel_hi:[1,0]
	v_pk_mul_f32 v[74:75], v[74:75], v[0:1] op_sel_hi:[1,0]
	v_pk_mul_f32 v[72:73], v[72:73], v[0:1] op_sel_hi:[1,0]
	v_pk_mul_f32 v[66:67], v[66:67], v[0:1] op_sel_hi:[1,0]
	v_pk_mul_f32 v[64:65], v[64:65], v[0:1] op_sel_hi:[1,0]
	v_pk_mul_f32 v[62:63], v[62:63], v[0:1] op_sel_hi:[1,0]
	v_pk_mul_f32 v[60:61], v[60:61], v[0:1] op_sel_hi:[1,0]
	v_mul_f32_e32 v195, v195, v0
.LBB0_1077:
	v_fma_f32 v0, v128, s23, -v193
	v_exp_f32_e32 v3, v0
	v_fma_f32 v0, v129, s23, -v193
	v_exp_f32_e32 v128, v0
	v_fma_f32 v0, v130, s23, -v193
	v_exp_f32_e32 v129, v0
	v_fma_f32 v0, v131, s23, -v193
	v_exp_f32_e32 v130, v0
	v_add_f32_e32 v0, v3, v128
	v_add_f32_e32 v2, v129, v130
	v_add_f32_e32 v0, v0, v2
	v_fma_f32 v2, v124, s23, -v193
	v_exp_f32_e32 v124, v2
	v_fma_f32 v2, v125, s23, -v193
	v_exp_f32_e32 v125, v2
	v_fma_f32 v2, v126, s23, -v193
	v_exp_f32_e32 v126, v2
	v_fma_f32 v2, v127, s23, -v193
	v_exp_f32_e32 v127, v2
	v_add_f32_e32 v2, v124, v125
	v_add_f32_e32 v0, 0, v0
	v_add_f32_e32 v131, v126, v127
	v_add_f32_e32 v2, v2, v131
	v_add_f32_e32 v0, v2, v0
	v_fma_f32 v2, v120, s23, -v193
	v_exp_f32_e32 v131, v2
	v_fma_f32 v2, v121, s23, -v193
	v_exp_f32_e32 v132, v2
	v_fma_f32 v2, v122, s23, -v193
	v_exp_f32_e32 v133, v2
	v_fma_f32 v2, v123, s23, -v193
	v_exp_f32_e32 v134, v2
	v_add_f32_e32 v2, v131, v132
	v_add_f32_e32 v120, v133, v134
	v_add_f32_e32 v2, v2, v120
	v_add_f32_e32 v0, v2, v0
	v_fma_f32 v2, v116, s23, -v193
	v_exp_f32_e32 v135, v2
	v_fma_f32 v2, v117, s23, -v193
	v_exp_f32_e32 v136, v2
	v_fma_f32 v2, v118, s23, -v193
	v_exp_f32_e32 v137, v2
	v_fma_f32 v2, v119, s23, -v193
	v_exp_f32_e32 v119, v2
	v_add_f32_e32 v2, v135, v136
	v_cvt_pk_bf16_f32 v120, v3, v128
	v_cvt_pk_bf16_f32 v121, v129, v130
	v_add_f32_e32 v116, v137, v119
	v_add_f32_e32 v2, v2, v116
	v_cvt_pk_bf16_f32 v122, v124, v125
	v_cvt_pk_bf16_f32 v123, v126, v127
	v_cvt_pk_bf16_f32 v116, v131, v132
	v_cvt_pk_bf16_f32 v117, v133, v134
	v_cvt_pk_bf16_f32 v118, v135, v136
	v_cvt_pk_bf16_f32 v119, v137, v119
	ds_read_b128 v[124:127], v171 offset:128
	ds_read_b128 v[128:131], v173
	s_waitcnt lgkmcnt(1)
	v_mfma_f32_16x16x32_bf16 v[124:127], v[124:127], v[12:15], 0
	ds_read_b128 v[132:135], v173 offset:1088
	ds_read_b128 v[136:139], v173 offset:8704
	v_add_f32_e32 v0, v2, v0
	s_waitcnt lgkmcnt(2)
	v_mfma_f32_16x16x32_bf16 v[124:127], v[128:131], v[16:19], v[124:127]
	ds_read_b128 v[128:131], v171 offset:1216
	v_mov_b32_e32 v2, v0
	v_mov_b32_e32 v222, v0
	s_nop 1
	v_permlane16_swap_b32_e32 v2, v222
	ds_read_b128 v[200:203], v173 offset:9792
	s_waitcnt lgkmcnt(1)
	v_mfma_f32_16x16x32_bf16 v[128:131], v[128:131], v[12:15], 0
	s_nop 2
	v_max_f32_e32 v3, v127, v127
	v_max_f32_e32 v196, v126, v126
	v_max_f32_e32 v3, v196, v3
	v_mfma_f32_16x16x32_bf16 v[128:131], v[132:135], v[16:19], v[128:131]
	ds_read_b128 v[132:135], v171 offset:8832
	v_max3_f32 v3, v124, v125, v3
	s_waitcnt lgkmcnt(2)
	v_add_f32_e32 v0, v2, v222
	s_waitcnt lgkmcnt(0)
	v_mfma_f32_16x16x32_bf16 v[132:135], v[132:135], v[12:15], 0
	s_nop 1
	v_max_f32_e32 v196, v131, v131
	v_max_f32_e32 v197, v130, v130
	v_max_f32_e32 v196, v197, v196
	v_mfma_f32_16x16x32_bf16 v[132:135], v[136:139], v[16:19], v[132:135]
	ds_read_b128 v[136:139], v171 offset:9920
	v_max3_f32 v196, v128, v129, v196
	v_max3_f32 v3, v3, s51, v196
	s_waitcnt lgkmcnt(0)
	v_mfma_f32_16x16x32_bf16 v[136:139], v[136:139], v[12:15], 0
	s_nop 2
	v_max_f32_e32 v196, v135, v135
	v_max_f32_e32 v197, v134, v134
	v_max_f32_e32 v196, v197, v196
	v_mfma_f32_16x16x32_bf16 v[136:139], v[200:203], v[16:19], v[136:139]
	v_max3_f32 v196, v132, v133, v196
	v_mov_b32_e32 v2, v0
	v_mov_b32_e32 v223, v0
	s_nop 1
	v_permlane32_swap_b32_e32 v2, v223
	s_nop 5
	v_max_f32_e32 v197, v139, v139
	v_max_f32_e32 v199, v138, v138
	v_max_f32_e32 v197, v199, v197
	v_max3_f32 v197, v136, v137, v197
	v_max3_f32 v3, v3, v196, v197
	v_mov_b32_e32 v196, v3
	v_mov_b32_e32 v224, v3
	s_nop 1
	v_permlane16_swap_b32_e32 v196, v224
	s_waitcnt lgkmcnt(0)
	v_max_f32_e32 v3, v196, v224
	v_mov_b32_e32 v196, v3
	v_mov_b32_e32 v225, v3
	s_nop 1
	v_permlane32_swap_b32_e32 v196, v225
	s_waitcnt lgkmcnt(0)
	v_max_f32_e32 v3, v196, v225
	v_mul_f32_e32 v3, 0x3e38aa3b, v3
	v_add_f32_e32 v196, 0x41000000, v161
	v_cmp_gt_f32_e32 vcc, v3, v196
	s_cbranch_vccz .LBB0_1079
	s_nop 0
	v_cndmask_b32_e32 v3, v161, v3, vcc
	v_sub_f32_e32 v161, v161, v3
	v_exp_f32_e32 v196, v161
	v_mov_b32_e32 v161, v3
	v_pk_mul_f32 v[110:111], v[110:111], v[196:197] op_sel_hi:[1,0]
	v_pk_mul_f32 v[108:109], v[108:109], v[196:197] op_sel_hi:[1,0]
	v_pk_mul_f32 v[102:103], v[102:103], v[196:197] op_sel_hi:[1,0]
	v_pk_mul_f32 v[100:101], v[100:101], v[196:197] op_sel_hi:[1,0]
	v_pk_mul_f32 v[94:95], v[94:95], v[196:197] op_sel_hi:[1,0]
	v_pk_mul_f32 v[92:93], v[92:93], v[196:197] op_sel_hi:[1,0]
	v_pk_mul_f32 v[86:87], v[86:87], v[196:197] op_sel_hi:[1,0]
	v_pk_mul_f32 v[84:85], v[84:85], v[196:197] op_sel_hi:[1,0]
	v_pk_mul_f32 v[78:79], v[78:79], v[196:197] op_sel_hi:[1,0]
	v_pk_mul_f32 v[76:77], v[76:77], v[196:197] op_sel_hi:[1,0]
	v_pk_mul_f32 v[70:71], v[70:71], v[196:197] op_sel_hi:[1,0]
	v_pk_mul_f32 v[68:69], v[68:69], v[196:197] op_sel_hi:[1,0]
	v_pk_mul_f32 v[58:59], v[58:59], v[196:197] op_sel_hi:[1,0]
	v_pk_mul_f32 v[56:57], v[56:57], v[196:197] op_sel_hi:[1,0]
	v_pk_mul_f32 v[54:55], v[54:55], v[196:197] op_sel_hi:[1,0]
	v_pk_mul_f32 v[52:53], v[52:53], v[196:197] op_sel_hi:[1,0]
	v_mul_f32_e32 v194, v194, v196
.LBB0_1079:
	v_add_f32_e32 v0, v2, v223
	v_fma_f32 v2, v124, s23, -v161
	v_exp_f32_e32 v124, v2
	v_fma_f32 v2, v125, s23, -v161
	v_exp_f32_e32 v125, v2
	v_fma_f32 v2, v126, s23, -v161
	v_exp_f32_e32 v126, v2
	v_fma_f32 v2, v127, s23, -v161
	v_exp_f32_e32 v127, v2
	v_add_f32_e32 v2, v124, v125
	v_add_f32_e32 v0, v195, v0
	v_add_f32_e32 v3, v126, v127
	v_add_f32_e32 v2, v2, v3
	v_fma_f32 v3, v128, s23, -v161
	v_exp_f32_e32 v195, v3
	v_fma_f32 v3, v129, s23, -v161
	v_exp_f32_e32 v196, v3
	v_fma_f32 v3, v130, s23, -v161
	v_exp_f32_e32 v197, v3
	v_fma_f32 v3, v131, s23, -v161
	v_exp_f32_e32 v131, v3
	v_add_f32_e32 v3, v195, v196
	v_add_f32_e32 v2, 0, v2
	v_add_f32_e32 v128, v197, v131
	v_add_f32_e32 v3, v3, v128
	v_add_f32_e32 v2, v3, v2
	v_fma_f32 v3, v132, s23, -v161
	v_exp_f32_e32 v132, v3
	v_fma_f32 v3, v133, s23, -v161
	v_exp_f32_e32 v133, v3
	v_fma_f32 v3, v134, s23, -v161
	v_exp_f32_e32 v134, v3
	v_fma_f32 v3, v135, s23, -v161
	v_exp_f32_e32 v135, v3
	v_add_f32_e32 v3, v132, v133
	v_add_f32_e32 v128, v134, v135
	v_add_f32_e32 v3, v3, v128
	v_add_f32_e32 v2, v3, v2
	v_fma_f32 v3, v136, s23, -v161
	v_exp_f32_e32 v136, v3
	v_fma_f32 v3, v137, s23, -v161
	v_exp_f32_e32 v137, v3
	v_fma_f32 v3, v138, s23, -v161
	v_exp_f32_e32 v138, v3
	v_fma_f32 v3, v139, s23, -v161
	v_exp_f32_e32 v139, v3
	v_add_f32_e32 v3, v136, v137
	v_add_f32_e32 v128, v138, v139
	v_add_f32_e32 v3, v3, v128
	v_add_f32_e32 v2, v3, v2
	v_mov_b32_e32 v3, v2
	v_mov_b32_e32 v228, v2
	s_nop 1
	v_permlane16_swap_b32_e32 v3, v228
	v_cvt_pk_bf16_f32 v128, v124, v125
	v_cvt_pk_bf16_f32 v129, v126, v127
	v_cvt_pk_bf16_f32 v130, v195, v196
	v_cvt_pk_bf16_f32 v131, v197, v131
	s_waitcnt lgkmcnt(0)
	v_add_f32_e32 v2, v3, v228
	v_mov_b32_e32 v3, v2
	v_mov_b32_e32 v229, v2
	s_nop 1
	v_permlane32_swap_b32_e32 v3, v229
	v_cvt_pk_bf16_f32 v124, v132, v133
	v_cvt_pk_bf16_f32 v125, v134, v135
	v_cvt_pk_bf16_f32 v126, v136, v137
	v_cvt_pk_bf16_f32 v127, v138, v139
	ds_read_b64_tr_b16 v[134:135], v174 offset:18560
	ds_read_b64_tr_b16 v[132:133], v174 offset:17408
	ds_read_b64_tr_b16 v[136:137], v174 offset:17440
	ds_read_b64_tr_b16 v[138:139], v174 offset:18592
	s_waitcnt lgkmcnt(2)
	v_mfma_f32_16x16x32_bf16 v[112:115], v[132:135], v[120:123], v[112:115]
	v_mfma_f32_16x16x32_bf16 v[108:111], v[132:135], v[128:131], v[108:111]
	ds_read_b64_tr_b16 v[132:133], v174 offset:17472
	ds_read_b64_tr_b16 v[134:135], v174 offset:18624
	s_waitcnt lgkmcnt(0)
	v_mfma_f32_16x16x32_bf16 v[96:99], v[132:135], v[120:123], v[96:99]
	v_mfma_f32_16x16x32_bf16 v[92:95], v[132:135], v[128:131], v[92:95]
	ds_read_b64_tr_b16 v[132:133], v174 offset:17504
	ds_read_b64_tr_b16 v[134:135], v174 offset:18656
	v_mfma_f32_16x16x32_bf16 v[104:107], v[136:139], v[120:123], v[104:107]
	v_mfma_f32_16x16x32_bf16 v[100:103], v[136:139], v[128:131], v[100:103]
	s_waitcnt lgkmcnt(0)
	v_mfma_f32_16x16x32_bf16 v[136:139], v[132:135], v[120:123], v[88:91]
	v_mfma_f32_16x16x32_bf16 v[132:135], v[132:135], v[128:131], v[84:87]
	s_nop 2
	ds_read_b64_tr_b16 v[84:85], v175 offset:17408
	ds_read_b64_tr_b16 v[86:87], v175 offset:18560
	s_waitcnt lgkmcnt(0)
	v_mfma_f32_16x16x32_bf16 v[204:207], v[84:87], v[128:131], v[76:79]
	s_nop 2
	ds_read_b64_tr_b16 v[76:77], v176 offset:17408
	ds_read_b64_tr_b16 v[78:79], v176 offset:18560
	s_waitcnt lgkmcnt(0)
	v_mfma_f32_16x16x32_bf16 v[208:211], v[76:79], v[128:131], v[68:71]
	s_nop 2
	ds_read_b64_tr_b16 v[68:69], v177 offset:17408
	ds_read_b64_tr_b16 v[70:71], v177 offset:18560
	s_waitcnt lgkmcnt(0)
	v_mfma_f32_16x16x32_bf16 v[216:219], v[68:71], v[128:131], v[56:59]
	s_nop 2
	ds_read_b64_tr_b16 v[56:57], v192 offset:17408
	ds_read_b64_tr_b16 v[58:59], v192 offset:18560
	v_mfma_f32_16x16x32_bf16 v[200:203], v[84:87], v[120:123], v[80:83]
	v_mfma_f32_16x16x32_bf16 v[72:75], v[76:79], v[120:123], v[72:75]
	v_mfma_f32_16x16x32_bf16 v[212:215], v[68:71], v[120:123], v[64:67]
	s_waitcnt lgkmcnt(0)
	v_mfma_f32_16x16x32_bf16 v[120:123], v[56:59], v[120:123], v[60:63]
	v_mfma_f32_16x16x32_bf16 v[128:131], v[56:59], v[128:131], v[52:55]
	s_min_u32 s4, s45, s44
	s_nop 1
	ds_read_b64_tr_b16 v[54:55], v174 offset:27776
	ds_read_b64_tr_b16 v[52:53], v174 offset:26624
	ds_read_b64_tr_b16 v[56:57], v174 offset:26656
	ds_read_b64_tr_b16 v[58:59], v174 offset:27808
	s_lshl_b32 s54, s4, 6
	s_cmp_lt_u32 s4, 4
	s_cselect_b64 s[48:49], -1, 0
	s_add_i32 s4, s54, 0xffffff00
	s_and_b64 s[52:53], s[48:49], exec
	s_cselect_b32 s58, s54, s4
	s_cselect_b32 s4, s27, s15
	s_cselect_b32 s54, s26, s14
	s_lshl_b64 s[52:53], s[58:59], 11
	s_add_u32 s54, s54, s52
	s_addc_u32 s4, s4, s53
	s_and_b64 s[48:49], s[48:49], exec
	s_waitcnt lgkmcnt(2)
	v_mfma_f32_16x16x32_bf16 v[68:71], v[52:55], v[116:119], v[112:115]
	s_cselect_b32 s49, s36, s24
	s_cselect_b32 s48, s37, s25
	s_add_u32 s52, s49, s52
	v_mfma_f32_16x16x32_bf16 v[80:83], v[52:55], v[124:127], v[108:111]
	ds_read_b64_tr_b16 v[52:53], v174 offset:26688
	ds_read_b64_tr_b16 v[54:55], v174 offset:27840
	s_addc_u32 s53, s48, s53
	s_add_u32 s48, s54, s40
	s_waitcnt lgkmcnt(2)
	v_mfma_f32_16x16x32_bf16 v[64:67], v[56:59], v[116:119], v[104:107]
	s_addc_u32 s49, s4, s41
	v_mfma_f32_16x16x32_bf16 v[76:79], v[56:59], v[124:127], v[100:103]
	ds_read_b64_tr_b16 v[56:57], v174 offset:26720
	ds_read_b64_tr_b16 v[58:59], v174 offset:27872
	ds_read_b64_tr_b16 v[60:61], v175 offset:26624
	ds_read_b64_tr_b16 v[62:63], v175 offset:27776
	ds_read_b64_tr_b16 v[100:101], v176 offset:26624
	ds_read_b64_tr_b16 v[102:103], v176 offset:27776
	s_waitcnt lgkmcnt(6)
	v_mfma_f32_16x16x32_bf16 v[84:87], v[52:55], v[116:119], v[96:99]
	v_mfma_f32_16x16x32_bf16 v[88:91], v[52:55], v[124:127], v[92:95]
	s_waitcnt lgkmcnt(2)
	v_mfma_f32_16x16x32_bf16 v[92:95], v[60:63], v[116:119], v[200:203]
	v_mfma_f32_16x16x32_bf16 v[96:99], v[60:63], v[124:127], v[204:207]
	s_waitcnt lgkmcnt(0)
	v_mfma_f32_16x16x32_bf16 v[60:63], v[100:103], v[116:119], v[72:75]
	v_mfma_f32_16x16x32_bf16 v[72:75], v[100:103], v[124:127], v[208:211]
	ds_read_b64_tr_b16 v[100:101], v177 offset:26624
	ds_read_b64_tr_b16 v[102:103], v177 offset:27776
	ds_read_b64_tr_b16 v[104:105], v192 offset:26624
	ds_read_b64_tr_b16 v[106:107], v192 offset:27776
	s_waitcnt lgkmcnt(0)
	s_barrier
	s_waitcnt vmcnt(7)
	ds_write_b128 v167, v[24:27]
	s_waitcnt vmcnt(6)
	ds_write_b128 v168, v[20:23]
	s_waitcnt vmcnt(5)
	ds_write_b128 v169, v[36:39] offset:17408
	s_waitcnt vmcnt(4)
	ds_write_b128 v170, v[40:43] offset:17408
	v_lshl_add_u64 v[20:21], v[152:153], 1, s[48:49]
	v_lshl_add_u64 v[20:21], v[140:141], 1, v[20:21]
	s_waitcnt lgkmcnt(0)
	s_barrier
	global_load_dwordx4 v[24:27], v[20:21], off
	v_lshl_add_u64 v[20:21], v[154:155], 1, s[48:49]
	s_add_u32 s48, s52, s40
	s_addc_u32 s49, s53, s41
	v_lshl_add_u64 v[36:37], v[150:151], 1, s[48:49]
	v_lshl_add_u64 v[40:41], v[156:157], 1, s[48:49]
	v_lshl_add_u64 v[20:21], v[142:143], 1, v[20:21]
	v_lshl_add_u64 v[36:37], v[144:145], 1, v[36:37]
	v_lshl_add_u64 v[40:41], v[146:147], 1, v[40:41]
	global_load_dwordx4 v[20:23], v[20:21], off
	v_mfma_f32_16x16x32_bf16 v[52:55], v[56:59], v[116:119], v[136:139]
	global_load_dwordx4 v[36:39], v[36:37], off
	s_nop 0
	global_load_dwordx4 v[40:43], v[40:41], off
	v_mfma_f32_16x16x32_bf16 v[108:111], v[100:103], v[116:119], v[212:215]
	v_mfma_f32_16x16x32_bf16 v[112:115], v[100:103], v[124:127], v[216:219]
	v_mfma_f32_16x16x32_bf16 v[100:103], v[104:107], v[116:119], v[120:123]
	ds_read_b128 v[116:119], v171
	s_nop 1
	ds_read_b128 v[120:123], v172
	s_waitcnt lgkmcnt(1)
	v_mfma_f32_16x16x32_bf16 v[116:119], v[116:119], v[4:7], 0
	s_waitcnt lgkmcnt(0)
	v_mfma_f32_16x16x32_bf16 v[116:119], v[120:123], v[8:11], v[116:119]
	ds_read_b128 v[120:123], v171 offset:1088
	v_mfma_f32_16x16x32_bf16 v[56:59], v[56:59], v[124:127], v[132:135]
	v_mfma_f32_16x16x32_bf16 v[104:107], v[104:107], v[124:127], v[128:131]
	ds_read_b128 v[124:127], v172 offset:1088
	s_nop 0
	ds_read_b128 v[132:135], v172 offset:9792
	s_waitcnt lgkmcnt(2)
	v_mfma_f32_16x16x32_bf16 v[120:123], v[120:123], v[4:7], 0
	ds_read_b128 v[128:131], v172 offset:8704
	s_waitcnt lgkmcnt(2)
	v_mfma_f32_16x16x32_bf16 v[120:123], v[124:127], v[8:11], v[120:123]
	ds_read_b128 v[124:127], v171 offset:8704
	s_waitcnt lgkmcnt(0)
	v_mfma_f32_16x16x32_bf16 v[124:127], v[124:127], v[4:7], 0
	v_mfma_f32_16x16x32_bf16 v[124:127], v[128:131], v[8:11], v[124:127]
	ds_read_b128 v[128:131], v171 offset:9792
	s_waitcnt lgkmcnt(0)
	v_mfma_f32_16x16x32_bf16 v[128:131], v[128:131], v[4:7], 0
	v_mfma_f32_16x16x32_bf16 v[128:131], v[132:135], v[8:11], v[128:131]
	v_max_f32_e32 v132, v119, v119
	v_max_f32_e32 v133, v118, v118
	v_max_f32_e32 v132, v133, v132
	v_max_f32_e32 v133, v123, v123
	v_max_f32_e32 v134, v122, v122
	v_max_f32_e32 v133, v134, v133
	v_max3_f32 v132, v116, v117, v132
	v_max3_f32 v133, v120, v121, v133
	v_max3_f32 v132, v132, s51, v133
	v_max_f32_e32 v133, v127, v127
	v_max_f32_e32 v134, v126, v126
	v_max_f32_e32 v133, v134, v133
	v_max_f32_e32 v134, v131, v131
	v_max_f32_e32 v135, v130, v130
	v_max_f32_e32 v134, v135, v134
	v_max3_f32 v133, v124, v125, v133
	v_max3_f32 v134, v128, v129, v134
	v_max3_f32 v132, v132, v133, v134
	v_mov_b32_e32 v133, v132
	v_mov_b32_e32 v230, v132
	s_nop 1
	v_permlane16_swap_b32_e32 v133, v230
	s_waitcnt lgkmcnt(0)
	v_max_f32_e32 v132, v133, v230
	v_mov_b32_e32 v133, v132
	v_mov_b32_e32 v231, v132
	s_nop 1
	v_permlane32_swap_b32_e32 v133, v231
	s_waitcnt lgkmcnt(0)
	v_max_f32_e32 v132, v133, v231
	v_mul_f32_e32 v132, 0x3e38aa3b, v132
	v_add_f32_e32 v133, 0x41000000, v193
	v_cmp_gt_f32_e32 vcc, v132, v133
	s_cbranch_vccz .LBB0_1081
	s_nop 0
	v_cndmask_b32_e32 v133, v193, v132, vcc
	v_sub_f32_e32 v132, v193, v133
	v_exp_f32_e32 v132, v132
	v_mov_b32_e32 v193, v133
	v_pk_mul_f32 v[70:71], v[70:71], v[132:133] op_sel_hi:[1,0]
	v_pk_mul_f32 v[68:69], v[68:69], v[132:133] op_sel_hi:[1,0]
	v_pk_mul_f32 v[66:67], v[66:67], v[132:133] op_sel_hi:[1,0]
	v_pk_mul_f32 v[64:65], v[64:65], v[132:133] op_sel_hi:[1,0]
	v_pk_mul_f32 v[86:87], v[86:87], v[132:133] op_sel_hi:[1,0]
	v_pk_mul_f32 v[84:85], v[84:85], v[132:133] op_sel_hi:[1,0]
	v_pk_mul_f32 v[54:55], v[54:55], v[132:133] op_sel_hi:[1,0]
	v_pk_mul_f32 v[52:53], v[52:53], v[132:133] op_sel_hi:[1,0]
	v_pk_mul_f32 v[94:95], v[94:95], v[132:133] op_sel_hi:[1,0]
	v_pk_mul_f32 v[92:93], v[92:93], v[132:133] op_sel_hi:[1,0]
	v_pk_mul_f32 v[62:63], v[62:63], v[132:133] op_sel_hi:[1,0]
	v_pk_mul_f32 v[60:61], v[60:61], v[132:133] op_sel_hi:[1,0]
	v_pk_mul_f32 v[110:111], v[110:111], v[132:133] op_sel_hi:[1,0]
	v_pk_mul_f32 v[108:109], v[108:109], v[132:133] op_sel_hi:[1,0]
	v_pk_mul_f32 v[102:103], v[102:103], v[132:133] op_sel_hi:[1,0]
	v_pk_mul_f32 v[100:101], v[100:101], v[132:133] op_sel_hi:[1,0]
	v_mul_f32_e32 v0, v0, v132
	v_xor_b32_e32 v132, 0x80000000, v133
	s_branch .LBB0_1082

.LBB0_1082:
	v_add_f32_e32 v2, v3, v229
	v_fmamk_f32 v3, v116, 0x3e38aa3b, v132
	v_exp_f32_e32 v116, v3
	v_fmamk_f32 v3, v117, 0x3e38aa3b, v132
	v_exp_f32_e32 v117, v3
	v_fmamk_f32 v3, v118, 0x3e38aa3b, v132
	v_exp_f32_e32 v118, v3
	v_fmamk_f32 v3, v119, 0x3e38aa3b, v132
	v_exp_f32_e32 v119, v3
	v_add_f32_e32 v3, v116, v117
	v_fmamk_f32 v120, v120, 0x3e38aa3b, v132
	v_add_f32_e32 v2, v194, v2
	v_add_f32_e32 v133, v118, v119
	v_add_f32_e32 v3, v3, v133
	v_exp_f32_e32 v133, v120
	v_fmamk_f32 v120, v121, 0x3e38aa3b, v132
	v_exp_f32_e32 v134, v120
	v_fmamk_f32 v120, v122, 0x3e38aa3b, v132
	v_exp_f32_e32 v135, v120
	v_fmamk_f32 v120, v123, 0x3e38aa3b, v132
	v_exp_f32_e32 v123, v120
	v_add_f32_e32 v120, v133, v134
	v_add_f32_e32 v3, 0, v3
	v_add_f32_e32 v121, v135, v123
	v_add_f32_e32 v120, v120, v121
	v_add_f32_e32 v3, v120, v3
	v_fmamk_f32 v120, v124, 0x3e38aa3b, v132
	v_exp_f32_e32 v124, v120
	v_fmamk_f32 v120, v125, 0x3e38aa3b, v132
	v_exp_f32_e32 v125, v120
	v_fmamk_f32 v120, v126, 0x3e38aa3b, v132
	v_exp_f32_e32 v126, v120
	v_fmamk_f32 v120, v127, 0x3e38aa3b, v132
	v_exp_f32_e32 v127, v120
	v_add_f32_e32 v120, v124, v125
	v_add_f32_e32 v121, v126, v127
	v_add_f32_e32 v120, v120, v121
	v_add_f32_e32 v3, v120, v3
	v_fmamk_f32 v120, v128, 0x3e38aa3b, v132
	v_exp_f32_e32 v128, v120
	v_fmamk_f32 v120, v129, 0x3e38aa3b, v132
	v_exp_f32_e32 v129, v120
	v_fmamk_f32 v120, v130, 0x3e38aa3b, v132
	v_fmac_f32_e32 v132, 0x3e38aa3b, v131
	v_exp_f32_e32 v130, v120
	v_exp_f32_e32 v131, v132
	v_add_f32_e32 v120, v128, v129
	v_add_f32_e32 v121, v130, v131
	v_add_f32_e32 v120, v120, v121
	v_add_f32_e32 v3, v120, v3
	v_mov_b32_e32 v120, v3
	v_mov_b32_e32 v220, v3
	s_nop 1
	v_permlane16_swap_b32_e32 v120, v220
	s_waitcnt lgkmcnt(0)
	v_add_f32_e32 v3, v120, v220
	v_cvt_pk_bf16_f32 v120, v116, v117
	v_cvt_pk_bf16_f32 v121, v118, v119
	v_cvt_pk_bf16_f32 v122, v133, v134
	v_cvt_pk_bf16_f32 v123, v135, v123
	v_cvt_pk_bf16_f32 v116, v124, v125
	v_cvt_pk_bf16_f32 v117, v126, v127
	v_cvt_pk_bf16_f32 v118, v128, v129
	v_cvt_pk_bf16_f32 v119, v130, v131
	ds_read_b128 v[124:127], v171 offset:128
	ds_read_b128 v[128:131], v173
	s_waitcnt lgkmcnt(1)
	v_mfma_f32_16x16x32_bf16 v[124:127], v[124:127], v[12:15], 0
	ds_read_b128 v[132:135], v173 offset:1088
	ds_read_b128 v[136:139], v173 offset:8704
	v_mov_b32_e32 v194, v3
	v_mov_b32_e32 v221, v3
	s_nop 1
	v_permlane32_swap_b32_e32 v194, v221
	s_waitcnt lgkmcnt(2)
	v_mfma_f32_16x16x32_bf16 v[124:127], v[128:131], v[16:19], v[124:127]
	ds_read_b128 v[128:131], v171 offset:1216
	ds_read_b128 v[200:203], v173 offset:9792
	s_waitcnt lgkmcnt(1)
	v_mfma_f32_16x16x32_bf16 v[128:131], v[128:131], v[12:15], 0
	s_nop 3
	v_max_f32_e32 v195, v127, v127
	v_max_f32_e32 v196, v126, v126
	v_max_f32_e32 v195, v196, v195
	v_mfma_f32_16x16x32_bf16 v[128:131], v[132:135], v[16:19], v[128:131]
	ds_read_b128 v[132:135], v171 offset:8832
	v_max3_f32 v195, v124, v125, v195
	s_waitcnt lgkmcnt(0)
	v_mfma_f32_16x16x32_bf16 v[132:135], v[132:135], v[12:15], 0
	s_nop 3
	v_max_f32_e32 v196, v131, v131
	v_max_f32_e32 v197, v130, v130
	v_max_f32_e32 v196, v197, v196
	v_mfma_f32_16x16x32_bf16 v[132:135], v[136:139], v[16:19], v[132:135]
	ds_read_b128 v[136:139], v171 offset:9920
	v_max3_f32 v196, v128, v129, v196
	v_max3_f32 v195, v195, s51, v196
	s_waitcnt lgkmcnt(0)
	v_mfma_f32_16x16x32_bf16 v[136:139], v[136:139], v[12:15], 0
	s_nop 2
	v_max_f32_e32 v196, v135, v135
	v_max_f32_e32 v197, v134, v134
	v_max_f32_e32 v196, v197, v196
	v_mfma_f32_16x16x32_bf16 v[136:139], v[200:203], v[16:19], v[136:139]
	v_max3_f32 v196, v132, v133, v196
	s_nop 6
	v_max_f32_e32 v197, v139, v139
	v_max_f32_e32 v199, v138, v138
	v_max_f32_e32 v197, v199, v197
	v_max3_f32 v197, v136, v137, v197
	v_max3_f32 v195, v195, v196, v197
	v_mov_b32_e32 v196, v195
	v_mov_b32_e32 v222, v195
	s_nop 1
	v_permlane16_swap_b32_e32 v196, v222
	s_waitcnt lgkmcnt(0)
	v_max_f32_e32 v195, v196, v222
	v_mov_b32_e32 v196, v195
	v_mov_b32_e32 v223, v195
	s_nop 1
	v_permlane32_swap_b32_e32 v196, v223
	s_waitcnt lgkmcnt(0)
	v_max_f32_e32 v195, v196, v223
	v_mul_f32_e32 v195, 0x3e38aa3b, v195
	v_add_f32_e32 v196, 0x41000000, v161
	v_cmp_gt_f32_e32 vcc, v195, v196
	s_cbranch_vccnz .LBB0_1073
	v_xor_b32_e32 v196, 0x80000000, v161
	s_branch .LBB0_1074
